# dynamic per-XCD unit hand-out (atomic counter) in FFN1/FFN2/W_o/gemm1 GEMM phases + saddr loads
# speedup vs baseline: 1.0080x; 1.0080x over previous
.LBB0_127:
	v_mov_b32_e32 v67, v169
	s_mov_b32 s11, s8
	v_lshrrev_b32_e32 v69, 4, v67
	v_ashrrev_i32_e32 v71, 3, v67
	v_lshrrev_b32_e32 v77, 1, v67
	v_and_b32_e32 v80, 4, v69
	v_and_b32_e32 v81, 3, v71
	v_and_b32_e32 v73, 7, v67
	v_xor_b32_e32 v75, v71, v67
	v_and_b32_e32 v77, 16, v77
	v_and_b32_e32 v79, 8, v69
	v_or_b32_e32 v82, v80, v81
	v_lshlrev_b32_e32 v75, 4, v75
	v_or3_b32 v77, v77, v79, v82
	v_bitop3_b32 v79, v80, v73, v81 bitop3:0x36
	v_lshlrev_b32_e32 v71, 7, v71
	v_lshlrev_b32_e32 v79, 4, v79
	v_and_or_b32 v122, v75, s24, v71
	v_lshl_or_b32 v121, v77, 7, v79
	s_waitcnt vmcnt(15)
	ds_write_b128 v122, v[34:37]
	s_waitcnt vmcnt(13)
	ds_write_b128 v121, v[38:41] offset:16384
	s_waitcnt vmcnt(11)
	ds_write_b128 v122, v[42:45] offset:4096
	s_waitcnt vmcnt(9)
	ds_write_b128 v121, v[46:49] offset:20480
	s_waitcnt vmcnt(7)
	ds_write_b128 v122, v[50:53] offset:8192
	s_waitcnt vmcnt(5)
	ds_write_b128 v121, v[54:57] offset:24576
	s_waitcnt vmcnt(3)
	ds_write_b128 v122, v[58:61] offset:12288
	s_waitcnt vmcnt(1)
	ds_write_b128 v121, v[62:65] offset:28672
	v_lshlrev_b32_e32 v34, 7, v67
	v_and_b32_e32 v35, 0x780, v34
	v_and_b32_e32 v123, 0x2780, v34
	v_bitop3_b32 v34, v69, v73, 3 bitop3:0x6c
	v_bfe_u32 v77, v67, 4, 2
	v_lshlrev_b32_e32 v124, 4, v34
	v_lshlrev_b32_e32 v34, 6, v67
	v_mov_b32_e32 v75, v1
	v_and_or_b32 v125, v34, s30, v35
	v_bitop3_b32 v34, v77, v73, 4 bitop3:0x36
	v_mov_b32_e32 v73, v1
	v_mov_b32_e32 v67, v1
	v_mov_b32_e32 v69, v1
	v_mov_b32_e32 v77, v1
	v_mov_b32_e32 v71, v1
	v_mov_b32_e32 v79, v1
	v_lshl_add_u64 v[100:101], v[74:75], 1, s[28:29]
	v_mov_b32_e32 v74, 0
	s_mov_b32 s5, s10
	s_mov_b32 s4, s9
	v_lshlrev_b32_e32 v126, 4, v34
	v_lshl_add_u64 v[98:99], v[72:73], 1, s[28:29]
	v_lshl_add_u64 v[102:103], v[76:77], 1, s[28:29]
	v_lshl_add_u64 v[104:105], v[78:79], 1, s[28:29]
	v_lshlrev_b64 v[106:107], 1, v[0:1]
	v_lshlrev_b64 v[108:109], 1, v[66:67]
	v_lshlrev_b64 v[110:111], 1, v[68:69]
	v_lshlrev_b64 v[112:113], 1, v[70:71]
	s_mov_b32 s8, -2
	s_mov_b64 s[42:43], s[72:73]
	v_mov_b32_e32 v75, v74
	v_mov_b32_e32 v76, v74
	v_mov_b32_e32 v77, v74
	v_mov_b32_e32 v62, v74
	v_mov_b32_e32 v63, v74
	v_mov_b32_e32 v64, v74
	v_mov_b32_e32 v65, v74
	v_mov_b32_e32 v66, v74
	v_mov_b32_e32 v67, v74
	v_mov_b32_e32 v68, v74
	v_mov_b32_e32 v69, v74
	v_mov_b32_e32 v58, v74
	v_mov_b32_e32 v59, v74
	v_mov_b32_e32 v60, v74
	v_mov_b32_e32 v61, v74
	v_mov_b32_e32 v70, v74
	v_mov_b32_e32 v71, v74
	v_mov_b32_e32 v72, v74
	v_mov_b32_e32 v73, v74
	v_mov_b32_e32 v54, v74
	v_mov_b32_e32 v55, v74
	v_mov_b32_e32 v56, v74
	v_mov_b32_e32 v57, v74
	v_mov_b32_e32 v78, v74
	v_mov_b32_e32 v79, v74
	v_mov_b32_e32 v80, v74
	v_mov_b32_e32 v81, v74
	v_mov_b32_e32 v50, v74
	v_mov_b32_e32 v51, v74
	v_mov_b32_e32 v52, v74
	v_mov_b32_e32 v53, v74
	v_mov_b32_e32 v82, v74
	v_mov_b32_e32 v83, v74
	v_mov_b32_e32 v84, v74
	v_mov_b32_e32 v85, v74
	v_mov_b32_e32 v46, v74
	v_mov_b32_e32 v47, v74
	v_mov_b32_e32 v48, v74
	v_mov_b32_e32 v49, v74
	v_mov_b32_e32 v86, v74
	v_mov_b32_e32 v87, v74
	v_mov_b32_e32 v88, v74
	v_mov_b32_e32 v89, v74
	v_mov_b32_e32 v42, v74
	v_mov_b32_e32 v43, v74
	v_mov_b32_e32 v44, v74
	v_mov_b32_e32 v45, v74
	v_mov_b32_e32 v90, v74
	v_mov_b32_e32 v91, v74
	v_mov_b32_e32 v92, v74
	v_mov_b32_e32 v93, v74
	v_mov_b32_e32 v38, v74
	v_mov_b32_e32 v39, v74
	v_mov_b32_e32 v40, v74
	v_mov_b32_e32 v41, v74
	v_mov_b32_e32 v94, v74
	v_mov_b32_e32 v95, v74
	v_mov_b32_e32 v96, v74
	v_mov_b32_e32 v97, v74
	v_mov_b32_e32 v34, v74
	v_mov_b32_e32 v35, v74
	v_mov_b32_e32 v36, v74
	v_mov_b32_e32 v37, v74
	s_waitcnt lgkmcnt(0)
	s_barrier
	v_add_u32_e32 v127, v124, v123
	v_add_u32_e32 v129, v124, v125
	v_add_u32_e32 v128, v126, v125
	v_add_u32_e32 v130, v126, v123
	v_readlane_b32 s100, v255, 36
	s_mul_i32 s100, s100, 0xa0
	s_and_b32 s101, s90, 7
	s_lshl_b32 s101, s101, 2
	s_add_u32 s100, s100, s101
	s_add_u32 s100, s100, 0x1a9d4b60
	s_add_u32 s98, s72, s100
	s_addc_u32 s99, s73, 0
	v_mov_b32_e32 v188, 0x10200
	v_mov_b32_e32 v187, 1
	v_cmp_eq_u32_e32 vcc, 0, v169
	s_mov_b64 s[100:101], exec
	s_and_b64 exec, exec, vcc
	s_cbranch_execz .Ldyn_skip_0
	global_atomic_add v187, v1, v187, s[98:99] sc0
.Ldyn_skip_0:
	s_mov_b64 exec, s[100:101]
.LBB0_128:
	s_setprio 1
	s_add_u32 s98, s42, s26
	s_addc_u32 s99, s43, 0
	s_add_u32 s100, s42, s27
	s_addc_u32 s101, s43, 0
	ds_read_b32 v189, v188
	ds_read_b128 v[132:135], v127 offset:16384
	ds_read_b128 v[152:155], v127 offset:18432
	ds_read_b128 v[160:163], v127 offset:20480
	ds_read_b128 v[164:167], v127 offset:22528
	ds_read_b128 v[140:143], v129
	ds_read_b128 v[144:147], v129 offset:2048
	ds_read_b128 v[148:151], v129 offset:4096
	ds_read_b128 v[156:159], v129 offset:6144
	s_waitcnt lgkmcnt(3)
	v_mfma_f32_16x16x32_bf16 v[34:37], v[132:135], v[140:143], v[34:37]
	global_load_dwordx4 v[194:197], v106, s[98:99] offset:256
	v_mfma_f32_16x16x32_bf16 v[94:97], v[152:155], v[140:143], v[94:97]
	ds_read_b128 v[198:201], v128
	v_mfma_f32_16x16x32_bf16 v[38:41], v[160:163], v[140:143], v[38:41]
	global_load_dwordx4 v[202:205], v98, s[100:101] offset:256
	v_mfma_f32_16x16x32_bf16 v[90:93], v[164:167], v[140:143], v[90:93]
	ds_read_b128 v[140:143], v128 offset:2048
	s_waitcnt lgkmcnt(4)
	v_mfma_f32_16x16x32_bf16 v[42:45], v[132:135], v[144:147], v[42:45]
	global_load_dwordx4 v[206:209], v108, s[98:99] offset:256
	v_mfma_f32_16x16x32_bf16 v[86:89], v[152:155], v[144:147], v[86:89]
	ds_read_b128 v[210:213], v128 offset:4096
	v_mfma_f32_16x16x32_bf16 v[46:49], v[160:163], v[144:147], v[46:49]
	global_load_dwordx4 v[214:217], v100, s[100:101] offset:256
	v_mfma_f32_16x16x32_bf16 v[82:85], v[164:167], v[144:147], v[82:85]
	ds_read_b128 v[144:147], v128 offset:6144
	s_waitcnt lgkmcnt(5)
	v_mfma_f32_16x16x32_bf16 v[50:53], v[132:135], v[148:151], v[50:53]
	global_load_dwordx4 v[218:221], v110, s[98:99] offset:256
	v_mfma_f32_16x16x32_bf16 v[78:81], v[152:155], v[148:151], v[78:81]
	ds_read_b128 v[222:225], v130 offset:16384
	v_mfma_f32_16x16x32_bf16 v[54:57], v[160:163], v[148:151], v[54:57]
	global_load_dwordx4 v[226:229], v102, s[100:101] offset:256
	v_mfma_f32_16x16x32_bf16 v[70:73], v[164:167], v[148:151], v[70:73]
	ds_read_b128 v[148:151], v130 offset:18432
	s_waitcnt lgkmcnt(6)
	v_mfma_f32_16x16x32_bf16 v[58:61], v[132:135], v[156:159], v[58:61]
	global_load_dwordx4 v[132:135], v112, s[98:99] offset:256
	v_mfma_f32_16x16x32_bf16 v[66:69], v[152:155], v[156:159], v[66:69]
	ds_read_b128 v[152:155], v130 offset:20480
	v_mfma_f32_16x16x32_bf16 v[62:65], v[160:163], v[156:159], v[62:65]
	global_load_dwordx4 v[160:163], v104, s[100:101] offset:256
	v_mfma_f32_16x16x32_bf16 v[74:77], v[164:167], v[156:159], v[74:77]
	ds_read_b128 v[156:159], v130 offset:22528
	s_waitcnt lgkmcnt(3)
	v_mfma_f32_16x16x32_bf16 v[34:37], v[222:225], v[198:201], v[34:37]
	s_waitcnt vmcnt(15)
	ds_write_b128 v122, v[2:5] offset:32768
	s_waitcnt lgkmcnt(3)
	v_mfma_f32_16x16x32_bf16 v[94:97], v[148:151], v[198:201], v[94:97]
	s_waitcnt lgkmcnt(2)
	v_mfma_f32_16x16x32_bf16 v[38:41], v[152:155], v[198:201], v[38:41]
	s_waitcnt vmcnt(14)
	ds_write_b128 v121, v[6:9] offset:49152
	s_waitcnt lgkmcnt(2)
	v_mfma_f32_16x16x32_bf16 v[90:93], v[156:159], v[198:201], v[90:93]
	v_mfma_f32_16x16x32_bf16 v[42:45], v[222:225], v[140:143], v[42:45]
	s_waitcnt vmcnt(13)
	ds_write_b128 v122, v[10:13] offset:36864
	v_mfma_f32_16x16x32_bf16 v[86:89], v[148:151], v[140:143], v[86:89]
	v_mfma_f32_16x16x32_bf16 v[46:49], v[152:155], v[140:143], v[46:49]
	s_waitcnt vmcnt(12)
	ds_write_b128 v121, v[14:17] offset:53248
	v_mfma_f32_16x16x32_bf16 v[82:85], v[156:159], v[140:143], v[82:85]
	v_mfma_f32_16x16x32_bf16 v[50:53], v[222:225], v[210:213], v[50:53]
	s_waitcnt vmcnt(11)
	ds_write_b128 v122, v[18:21] offset:40960
	v_mfma_f32_16x16x32_bf16 v[78:81], v[148:151], v[210:213], v[78:81]
	v_mfma_f32_16x16x32_bf16 v[54:57], v[152:155], v[210:213], v[54:57]
	s_waitcnt vmcnt(10)
	ds_write_b128 v121, v[22:25] offset:57344
	v_mfma_f32_16x16x32_bf16 v[70:73], v[156:159], v[210:213], v[70:73]
	v_mfma_f32_16x16x32_bf16 v[58:61], v[222:225], v[144:147], v[58:61]
	s_waitcnt vmcnt(9)
	ds_write_b128 v122, v[26:29] offset:45056
	v_mfma_f32_16x16x32_bf16 v[66:69], v[148:151], v[144:147], v[66:69]
	v_mfma_f32_16x16x32_bf16 v[62:65], v[152:155], v[144:147], v[62:65]
	s_waitcnt vmcnt(8)
	ds_write_b128 v121, v[30:33] offset:61440
	v_mfma_f32_16x16x32_bf16 v[74:77], v[156:159], v[144:147], v[74:77]
	s_setprio 0
	s_waitcnt lgkmcnt(0)
	s_barrier
	s_setprio 1
	ds_read_b128 v[26:29], v127 offset:49152
	ds_read_b128 v[30:33], v127 offset:51200
	ds_read_b128 v[148:151], v127 offset:53248
	ds_read_b128 v[152:155], v127 offset:55296
	ds_read_b128 v[10:13], v129 offset:32768
	ds_read_b128 v[18:21], v129 offset:34816
	ds_read_b128 v[140:143], v129 offset:36864
	ds_read_b128 v[144:147], v129 offset:38912
	s_waitcnt lgkmcnt(3)
	v_mfma_f32_16x16x32_bf16 v[34:37], v[26:29], v[10:13], v[34:37]
	global_load_dwordx4 v[2:5], v106, s[98:99] offset:384
	v_mfma_f32_16x16x32_bf16 v[94:97], v[30:33], v[10:13], v[94:97]
	ds_read_b128 v[156:159], v128 offset:32768
	v_mfma_f32_16x16x32_bf16 v[38:41], v[148:151], v[10:13], v[38:41]
	global_load_dwordx4 v[6:9], v98, s[100:101] offset:384
	v_mfma_f32_16x16x32_bf16 v[90:93], v[152:155], v[10:13], v[90:93]
	ds_read_b128 v[164:167], v128 offset:34816
	s_waitcnt lgkmcnt(4)
	v_mfma_f32_16x16x32_bf16 v[42:45], v[26:29], v[18:21], v[42:45]
	global_load_dwordx4 v[10:13], v108, s[98:99] offset:384
	v_mfma_f32_16x16x32_bf16 v[86:89], v[30:33], v[18:21], v[86:89]
	ds_read_b128 v[198:201], v128 offset:36864
	v_mfma_f32_16x16x32_bf16 v[46:49], v[148:151], v[18:21], v[46:49]
	global_load_dwordx4 v[14:17], v100, s[100:101] offset:384
	v_mfma_f32_16x16x32_bf16 v[82:85], v[152:155], v[18:21], v[82:85]
	ds_read_b128 v[210:213], v128 offset:38912
	s_waitcnt lgkmcnt(5)
	v_mfma_f32_16x16x32_bf16 v[50:53], v[26:29], v[140:143], v[50:53]
	global_load_dwordx4 v[18:21], v110, s[98:99] offset:384
	v_mfma_f32_16x16x32_bf16 v[78:81], v[30:33], v[140:143], v[78:81]
	ds_read_b128 v[222:225], v130 offset:49152
	v_mfma_f32_16x16x32_bf16 v[54:57], v[148:151], v[140:143], v[54:57]
	global_load_dwordx4 v[22:25], v102, s[100:101] offset:384
	v_mfma_f32_16x16x32_bf16 v[70:73], v[152:155], v[140:143], v[70:73]
	ds_read_b128 v[140:143], v130 offset:51200
	s_waitcnt lgkmcnt(6)
	v_mfma_f32_16x16x32_bf16 v[58:61], v[26:29], v[144:147], v[58:61]
	global_load_dwordx4 v[26:29], v112, s[98:99] offset:384
	v_mfma_f32_16x16x32_bf16 v[66:69], v[30:33], v[144:147], v[66:69]
	ds_read_b128 v[230:233], v130 offset:53248
	v_mfma_f32_16x16x32_bf16 v[62:65], v[148:151], v[144:147], v[62:65]
	global_load_dwordx4 v[30:33], v104, s[100:101] offset:384
	v_mfma_f32_16x16x32_bf16 v[74:77], v[152:155], v[144:147], v[74:77]
	ds_read_b128 v[144:147], v130 offset:55296
	s_waitcnt lgkmcnt(3)
	v_mfma_f32_16x16x32_bf16 v[34:37], v[222:225], v[156:159], v[34:37]
	s_waitcnt vmcnt(15)
	ds_write_b128 v122, v[194:197]
	s_waitcnt lgkmcnt(3)
	v_mfma_f32_16x16x32_bf16 v[94:97], v[140:143], v[156:159], v[94:97]
	s_waitcnt lgkmcnt(2)
	v_mfma_f32_16x16x32_bf16 v[38:41], v[230:233], v[156:159], v[38:41]
	s_waitcnt vmcnt(14)
	ds_write_b128 v121, v[202:205] offset:16384
	s_waitcnt lgkmcnt(2)
	v_mfma_f32_16x16x32_bf16 v[90:93], v[144:147], v[156:159], v[90:93]
	v_mfma_f32_16x16x32_bf16 v[42:45], v[222:225], v[164:167], v[42:45]
	s_waitcnt vmcnt(13)
	ds_write_b128 v122, v[206:209] offset:4096
	v_mfma_f32_16x16x32_bf16 v[86:89], v[140:143], v[164:167], v[86:89]
	v_mfma_f32_16x16x32_bf16 v[46:49], v[230:233], v[164:167], v[46:49]
	s_waitcnt vmcnt(12)
	ds_write_b128 v121, v[214:217] offset:20480
	v_mfma_f32_16x16x32_bf16 v[82:85], v[144:147], v[164:167], v[82:85]
	v_mfma_f32_16x16x32_bf16 v[50:53], v[222:225], v[198:201], v[50:53]
	s_waitcnt vmcnt(11)
	ds_write_b128 v122, v[218:221] offset:8192
	v_mfma_f32_16x16x32_bf16 v[78:81], v[140:143], v[198:201], v[78:81]
	v_mfma_f32_16x16x32_bf16 v[54:57], v[230:233], v[198:201], v[54:57]
	s_waitcnt vmcnt(10)
	ds_write_b128 v121, v[226:229] offset:24576
	v_mfma_f32_16x16x32_bf16 v[70:73], v[144:147], v[198:201], v[70:73]
	v_mfma_f32_16x16x32_bf16 v[58:61], v[222:225], v[210:213], v[58:61]
	s_waitcnt vmcnt(9)
	ds_write_b128 v122, v[132:135] offset:12288
	v_mfma_f32_16x16x32_bf16 v[66:69], v[140:143], v[210:213], v[66:69]
	v_mfma_f32_16x16x32_bf16 v[62:65], v[230:233], v[210:213], v[62:65]
	s_waitcnt vmcnt(8)
	ds_write_b128 v121, v[160:163] offset:28672
	v_mfma_f32_16x16x32_bf16 v[74:77], v[144:147], v[210:213], v[74:77]
	s_mov_b64 exec, vcc
	ds_write_b32 v188, v187
	s_mov_b64 exec, -1
	s_setprio 0
	s_add_i32 s8, s8, 2
	s_add_u32 s42, s42, 0x100
	s_addc_u32 s43, s43, 0
	s_cmp_lt_u32 s8, 40
	s_waitcnt lgkmcnt(0)
	s_barrier
	s_cbranch_scc1 .LBB0_128
	v_readfirstlane_b32 s8, v189
	s_nop 3
	s_add_i32 s8, s8, s2
	s_cmpk_lt_u32 s8, 0x100
	s_cselect_b32 s10, s8, s11
	s_lshr_b32 s9, s10, 3
	s_and_b32 s9, s9, 0x1fffff8
	s_add_i32 s9, s9, s21
	s_and_b32 s11, s10, 7
	s_or_b32 s9, s9, s11
	v_mov_b32_e32 v0, v169
	s_lshl_b32 s9, s9, 7
	s_movk_i32 s11, 0xb00
	v_lshrrev_b32_e32 v98, 3, v0
	v_add_u32_e32 v98, s9, v98
	v_lshlrev_b32_e32 v0, 3, v0
	v_mul_lo_u32 v98, v98, s11
	s_lshl_b32 s10, s10, 4
	v_and_or_b32 v0, v0, 56, v98
	v_mov_b32_e32 v98, v169
	s_and_b32 s10, s10, 0x380
	s_cmpk_gt_u32 s8, 0xff
	v_lshrrev_b32_e32 v99, 3, v98
	v_add_u32_e32 v99, s10, v99
	v_lshlrev_b32_e32 v98, 3, v98
	v_mul_lo_u32 v99, v99, s11
	v_and_or_b32 v164, v98, 56, v99
	v_add_u32_e32 v114, 0x16000, v0
	v_add_u32_e32 v124, 0x2c000, v0
	v_add_u32_e32 v136, 0x42000, v0
	v_add_u32_e32 v174, 0x16000, v164
	v_add_u32_e32 v176, 0x2c000, v164
	v_add_u32_e32 v178, 0x42000, v164
	s_setprio 1
	ds_read_b128 v[98:101], v127 offset:16384
	ds_read_b128 v[110:113], v127 offset:18432
	ds_read_b128 v[144:147], v127 offset:20480
	ds_read_b128 v[148:151], v127 offset:22528
	ds_read_b128 v[102:105], v129
	ds_read_b128 v[106:109], v129 offset:2048
	ds_read_b128 v[132:135], v129 offset:4096
	ds_read_b128 v[140:143], v129 offset:6144
	v_readlane_b32 s14, v254, 33
	v_readlane_b32 s15, v254, 34
	v_mov_b32_e32 v165, v1
	v_mov_b32_e32 v115, v1
	v_mov_b32_e32 v175, v1
	v_mov_b32_e32 v125, v1
	v_mov_b32_e32 v177, v1
	v_mov_b32_e32 v137, v1
	v_mov_b32_e32 v179, v1
	v_lshl_add_u64 v[180:181], v[0:1], 1, s[14:15]
	v_lshl_add_u64 v[186:187], v[164:165], 1, s[38:39]
	v_lshl_add_u64 v[114:115], v[114:115], 1, s[14:15]
	v_lshl_add_u64 v[174:175], v[174:175], 1, s[38:39]
	v_lshl_add_u64 v[188:189], v[124:125], 1, s[14:15]
	v_lshl_add_u64 v[176:177], v[176:177], 1, s[38:39]
	v_lshl_add_u64 v[136:137], v[136:137], 1, s[14:15]
	v_lshl_add_u64 v[178:179], v[178:179], 1, s[38:39]
	s_waitcnt lgkmcnt(3)
	v_mfma_f32_16x16x32_bf16 v[152:155], v[98:101], v[102:105], v[34:37]
	s_nop 2
	global_load_dwordx4 v[34:37], v[180:181], off
	v_mfma_f32_16x16x32_bf16 v[94:97], v[110:113], v[102:105], v[94:97]
	ds_read_b128 v[156:159], v128
	v_mfma_f32_16x16x32_bf16 v[160:163], v[144:147], v[102:105], v[38:41]
	s_nop 2
	global_load_dwordx4 v[38:41], v[186:187], off
	v_mfma_f32_16x16x32_bf16 v[90:93], v[148:151], v[102:105], v[90:93]
	ds_read_b128 v[102:105], v128 offset:2048
	s_waitcnt lgkmcnt(4)
	v_mfma_f32_16x16x32_bf16 v[164:167], v[98:101], v[106:109], v[42:45]
	s_nop 2
	global_load_dwordx4 v[42:45], v[114:115], off
	v_mfma_f32_16x16x32_bf16 v[86:89], v[110:113], v[106:109], v[86:89]
	ds_read_b128 v[194:197], v128 offset:4096
	v_mfma_f32_16x16x32_bf16 v[198:201], v[144:147], v[106:109], v[46:49]
	s_nop 2
	global_load_dwordx4 v[46:49], v[174:175], off
	v_mfma_f32_16x16x32_bf16 v[82:85], v[148:151], v[106:109], v[82:85]
	ds_read_b128 v[106:109], v128 offset:6144
	s_waitcnt lgkmcnt(5)
	v_mfma_f32_16x16x32_bf16 v[202:205], v[98:101], v[132:135], v[50:53]
	s_nop 2
	global_load_dwordx4 v[50:53], v[188:189], off
	v_mfma_f32_16x16x32_bf16 v[78:81], v[110:113], v[132:135], v[78:81]
	ds_read_b128 v[206:209], v130 offset:16384
	v_mfma_f32_16x16x32_bf16 v[210:213], v[144:147], v[132:135], v[54:57]
	s_nop 2
	global_load_dwordx4 v[54:57], v[176:177], off
	v_mfma_f32_16x16x32_bf16 v[70:73], v[148:151], v[132:135], v[70:73]
	ds_read_b128 v[132:135], v130 offset:18432
	s_waitcnt lgkmcnt(6)
	v_mfma_f32_16x16x32_bf16 v[98:101], v[98:101], v[140:143], v[58:61]
	s_nop 2
	global_load_dwordx4 v[58:61], v[136:137], off
	v_mfma_f32_16x16x32_bf16 v[66:69], v[110:113], v[140:143], v[66:69]
	ds_read_b128 v[110:113], v130 offset:20480
	v_mfma_f32_16x16x32_bf16 v[144:147], v[144:147], v[140:143], v[62:65]
	s_nop 2
	global_load_dwordx4 v[62:65], v[178:179], off
	v_mfma_f32_16x16x32_bf16 v[74:77], v[148:151], v[140:143], v[74:77]
	ds_read_b128 v[140:143], v130 offset:22528
	s_waitcnt lgkmcnt(3)
	v_mfma_f32_16x16x32_bf16 v[148:151], v[206:209], v[156:159], v[152:155]
	s_waitcnt vmcnt(15)
	ds_write_b128 v122, v[2:5] offset:32768
	s_waitcnt lgkmcnt(3)
	v_mfma_f32_16x16x32_bf16 v[94:97], v[132:135], v[156:159], v[94:97]
	s_waitcnt lgkmcnt(2)
	v_mfma_f32_16x16x32_bf16 v[152:155], v[110:113], v[156:159], v[160:163]
	s_waitcnt vmcnt(14)
	ds_write_b128 v121, v[6:9] offset:49152
	s_waitcnt lgkmcnt(2)
	v_mfma_f32_16x16x32_bf16 v[90:93], v[140:143], v[156:159], v[90:93]
	v_mfma_f32_16x16x32_bf16 v[156:159], v[206:209], v[102:105], v[164:167]
	s_waitcnt vmcnt(13)
	ds_write_b128 v122, v[10:13] offset:36864
	v_mfma_f32_16x16x32_bf16 v[86:89], v[132:135], v[102:105], v[86:89]
	v_mfma_f32_16x16x32_bf16 v[160:163], v[110:113], v[102:105], v[198:201]
	s_waitcnt vmcnt(12)
	ds_write_b128 v121, v[14:17] offset:53248
	v_mfma_f32_16x16x32_bf16 v[82:85], v[140:143], v[102:105], v[82:85]
	v_mfma_f32_16x16x32_bf16 v[102:105], v[206:209], v[194:197], v[202:205]
	s_waitcnt vmcnt(11)
	ds_write_b128 v122, v[18:21] offset:40960
	v_mfma_f32_16x16x32_bf16 v[78:81], v[132:135], v[194:197], v[78:81]
	v_mfma_f32_16x16x32_bf16 v[164:167], v[110:113], v[194:197], v[210:213]
	s_waitcnt vmcnt(10)
	ds_write_b128 v121, v[22:25] offset:57344
	v_mfma_f32_16x16x32_bf16 v[70:73], v[140:143], v[194:197], v[70:73]
	v_mfma_f32_16x16x32_bf16 v[98:101], v[206:209], v[106:109], v[98:101]
	s_waitcnt vmcnt(9)
	ds_write_b128 v122, v[26:29] offset:45056
	v_mfma_f32_16x16x32_bf16 v[66:69], v[132:135], v[106:109], v[66:69]
	v_mfma_f32_16x16x32_bf16 v[110:113], v[110:113], v[106:109], v[144:147]
	s_waitcnt vmcnt(8)
	ds_write_b128 v121, v[30:33] offset:61440
	v_mfma_f32_16x16x32_bf16 v[74:77], v[140:143], v[106:109], v[74:77]
	s_setprio 0
	s_waitcnt lgkmcnt(0)
	s_barrier
	s_setprio 1
	ds_read_b128 v[26:29], v127 offset:49152
	ds_read_b128 v[30:33], v127 offset:51200
	ds_read_b128 v[132:135], v127 offset:53248
	ds_read_b128 v[140:143], v127 offset:55296
	ds_read_b128 v[10:13], v129 offset:32768
	ds_read_b128 v[18:21], v129 offset:34816
	ds_read_b128 v[106:109], v129 offset:36864
	ds_read_b128 v[122:125], v129 offset:38912
	s_waitcnt lgkmcnt(3)
	v_mfma_f32_16x16x32_bf16 v[144:147], v[26:29], v[10:13], v[148:151]
	global_load_dwordx4 v[2:5], v[180:181], off offset:128
	v_mfma_f32_16x16x32_bf16 v[94:97], v[30:33], v[10:13], v[94:97]
	s_nop 0
	ds_read_b128 v[148:151], v128 offset:32768
	v_mfma_f32_16x16x32_bf16 v[152:155], v[132:135], v[10:13], v[152:155]
	global_load_dwordx4 v[6:9], v[186:187], off offset:128
	v_mfma_f32_16x16x32_bf16 v[90:93], v[140:143], v[10:13], v[90:93]
	ds_read_b128 v[194:197], v128 offset:34816
	s_waitcnt lgkmcnt(4)
	v_mfma_f32_16x16x32_bf16 v[156:159], v[26:29], v[18:21], v[156:159]
	global_load_dwordx4 v[10:13], v[114:115], off offset:128
	v_mfma_f32_16x16x32_bf16 v[86:89], v[30:33], v[18:21], v[86:89]
	ds_read_b128 v[198:201], v128 offset:36864
	v_mfma_f32_16x16x32_bf16 v[160:163], v[132:135], v[18:21], v[160:163]
	global_load_dwordx4 v[14:17], v[174:175], off offset:128
	v_mfma_f32_16x16x32_bf16 v[82:85], v[140:143], v[18:21], v[82:85]
	ds_read_b128 v[126:129], v128 offset:38912
	s_waitcnt lgkmcnt(5)
	v_mfma_f32_16x16x32_bf16 v[202:205], v[26:29], v[106:109], v[102:105]
	global_load_dwordx4 v[18:21], v[188:189], off offset:128
	v_mfma_f32_16x16x32_bf16 v[78:81], v[30:33], v[106:109], v[78:81]
	ds_read_b128 v[206:209], v130 offset:49152
	v_mfma_f32_16x16x32_bf16 v[164:167], v[132:135], v[106:109], v[164:167]
	global_load_dwordx4 v[22:25], v[176:177], off offset:128
	v_mfma_f32_16x16x32_bf16 v[70:73], v[140:143], v[106:109], v[70:73]
	ds_read_b128 v[210:213], v130 offset:51200
	s_waitcnt lgkmcnt(6)
	v_mfma_f32_16x16x32_bf16 v[214:217], v[26:29], v[122:125], v[98:101]
	global_load_dwordx4 v[26:29], v[136:137], off offset:128
	v_mfma_f32_16x16x32_bf16 v[66:69], v[30:33], v[122:125], v[66:69]
	ds_read_b128 v[218:221], v130 offset:53248
	v_mfma_f32_16x16x32_bf16 v[110:113], v[132:135], v[122:125], v[110:113]
	global_load_dwordx4 v[30:33], v[178:179], off offset:128
	v_mfma_f32_16x16x32_bf16 v[122:125], v[140:143], v[122:125], v[74:77]
	s_waitcnt lgkmcnt(2)
	v_mfma_f32_16x16x32_bf16 v[132:135], v[206:209], v[148:151], v[144:147]
	s_waitcnt lgkmcnt(0)
	v_mfma_f32_16x16x32_bf16 v[144:147], v[218:221], v[148:151], v[152:155]
	s_nop 2
	ds_read_b128 v[152:155], v130 offset:55296
	v_mfma_f32_16x16x32_bf16 v[140:143], v[210:213], v[148:151], v[94:97]
	s_waitcnt lgkmcnt(0)
	v_mfma_f32_16x16x32_bf16 v[148:151], v[152:155], v[148:151], v[90:93]
	v_mfma_f32_16x16x32_bf16 v[98:101], v[152:155], v[194:197], v[82:85]
	v_mfma_f32_16x16x32_bf16 v[90:93], v[210:213], v[198:201], v[78:81]
	v_mfma_f32_16x16x32_bf16 v[82:85], v[152:155], v[198:201], v[70:73]
	v_mfma_f32_16x16x32_bf16 v[78:81], v[206:209], v[126:129], v[214:217]
	v_mfma_f32_16x16x32_bf16 v[74:77], v[210:213], v[126:129], v[66:69]
	v_mfma_f32_16x16x32_bf16 v[66:69], v[218:221], v[126:129], v[110:113]
	v_mfma_f32_16x16x32_bf16 v[70:73], v[152:155], v[126:129], v[122:125]
	v_mfma_f32_16x16x32_bf16 v[156:159], v[206:209], v[194:197], v[156:159]
	v_mfma_f32_16x16x32_bf16 v[106:109], v[210:213], v[194:197], v[86:89]
	v_mfma_f32_16x16x32_bf16 v[102:105], v[218:221], v[194:197], v[160:163]
	v_mfma_f32_16x16x32_bf16 v[94:97], v[206:209], v[198:201], v[202:205]
	v_mfma_f32_16x16x32_bf16 v[86:89], v[218:221], v[198:201], v[164:167]
	s_setprio 0
	v_add_u32_e32 v110, s4, v116
	v_ashrrev_i32_e32 v111, 31, v110
	v_readlane_b32 s44, v253, 18
	v_lshlrev_b64 v[112:113], 12, v[110:111]
	v_or_b32_e32 v0, s5, v117
	v_readlane_b32 s58, v253, 32
	v_readlane_b32 s59, v253, 33
	v_lshlrev_b64 v[114:115], 2, v[0:1]
	v_lshl_add_u64 v[166:167], v[110:111], 3, s[0:1]
	v_lshl_add_u64 v[112:113], s[58:59], 0, v[112:113]
	v_lshl_add_u64 v[164:165], v[112:113], 0, v[114:115]
	s_barrier
	global_load_dwordx2 v[130:131], v[166:167], off
	global_load_dwordx4 v[122:125], v[164:165], off
	v_lshl_add_u64 v[112:113], s[34:35], 0, v[114:115]
	v_lshl_add_u64 v[110:111], s[40:41], 0, v[114:115]
	global_load_dwordx4 v[126:129], v[112:113], off
	global_load_dwordx4 v[152:155], v[110:111], off
	s_mov_b32 s14, 0x3fb504f3
	global_load_dwordx4 v[160:163], v[164:165], off offset:16
	s_mov_b64 s[42:43], -1
	v_readlane_b32 s45, v253, 19
	v_readlane_b32 s46, v253, 20
	v_readlane_b32 s47, v253, 21
	v_readlane_b32 s48, v253, 22
	v_readlane_b32 s49, v253, 23
	v_readlane_b32 s50, v253, 24
	v_readlane_b32 s51, v253, 25
	v_readlane_b32 s52, v253, 26
	v_readlane_b32 s53, v253, 27
	v_readlane_b32 s54, v253, 28
	v_readlane_b32 s55, v253, 29
	v_readlane_b32 s56, v253, 30
	v_readlane_b32 s57, v253, 31
	s_waitcnt vmcnt(3)
	v_pk_add_f32 v[122:123], v[122:123], v[130:131] op_sel_hi:[1,0] neg_lo:[0,1] neg_hi:[0,1]
	v_pk_add_f32 v[124:125], v[124:125], v[130:131] op_sel_hi:[1,0] neg_lo:[0,1] neg_hi:[0,1]
	v_pk_mul_f32 v[122:123], v[122:123], v[130:131] op_sel:[0,1]
	v_pk_mul_f32 v[124:125], v[124:125], v[130:131] op_sel:[0,1]
	s_waitcnt vmcnt(1)
	v_pk_fma_f32 v[122:123], v[122:123], v[126:127], v[152:153]
	v_pk_fma_f32 v[124:125], v[124:125], v[128:129], v[154:155]
	v_pk_fma_f32 v[122:123], v[122:123], s[14:15], v[132:133] op_sel_hi:[1,0,1]
	v_pk_fma_f32 v[124:125], v[124:125], s[14:15], v[134:135] op_sel_hi:[1,0,1]
	global_store_dwordx4 v[164:165], v[122:125], off
	global_load_dwordx2 v[134:135], v[166:167], off
	global_load_dwordx4 v[126:129], v[110:111], off offset:16
	global_load_dwordx4 v[130:133], v[164:165], off offset:128
	s_waitcnt vmcnt(2)
	v_pk_add_f32 v[136:137], v[160:161], v[134:135] op_sel_hi:[1,0] neg_lo:[0,1] neg_hi:[0,1]
	global_load_dwordx4 v[122:125], v[112:113], off offset:16
	v_pk_add_f32 v[152:153], v[162:163], v[134:135] op_sel_hi:[1,0] neg_lo:[0,1] neg_hi:[0,1]
	v_pk_mul_f32 v[136:137], v[136:137], v[134:135] op_sel:[0,1]
	v_pk_mul_f32 v[134:135], v[152:153], v[134:135] op_sel:[0,1]
	s_waitcnt vmcnt(0)
	v_pk_fma_f32 v[122:123], v[136:137], v[122:123], v[126:127]
	v_pk_fma_f32 v[124:125], v[134:135], v[124:125], v[128:129]
	v_pk_fma_f32 v[122:123], v[122:123], s[14:15], v[140:141] op_sel_hi:[1,0,1]
	v_pk_fma_f32 v[124:125], v[124:125], s[14:15], v[142:143] op_sel_hi:[1,0,1]
	global_store_dwordx4 v[164:165], v[122:125], off offset:16
	global_load_dwordx2 v[140:141], v[166:167], off
	global_load_dwordx4 v[126:129], v[110:111], off offset:128
	global_load_dwordx4 v[134:137], v[164:165], off offset:144
	s_waitcnt vmcnt(2)
	v_pk_add_f32 v[130:131], v[130:131], v[140:141] op_sel_hi:[1,0] neg_lo:[0,1] neg_hi:[0,1]
	global_load_dwordx4 v[122:125], v[112:113], off offset:128
	v_pk_add_f32 v[132:133], v[132:133], v[140:141] op_sel_hi:[1,0] neg_lo:[0,1] neg_hi:[0,1]
	v_pk_mul_f32 v[130:131], v[130:131], v[140:141] op_sel:[0,1]
	v_pk_mul_f32 v[132:133], v[132:133], v[140:141] op_sel:[0,1]
	s_waitcnt vmcnt(0)
	v_pk_fma_f32 v[122:123], v[130:131], v[122:123], v[126:127]
	v_pk_fma_f32 v[124:125], v[132:133], v[124:125], v[128:129]
	v_pk_fma_f32 v[122:123], v[122:123], s[14:15], v[144:145] op_sel_hi:[1,0,1]
	v_pk_fma_f32 v[124:125], v[124:125], s[14:15], v[146:147] op_sel_hi:[1,0,1]
	global_store_dwordx4 v[164:165], v[122:125], off offset:128
	global_load_dwordx2 v[140:141], v[166:167], off
	global_load_dwordx4 v[126:129], v[110:111], off offset:144
	v_add_u32_e32 v130, s4, v118
	global_load_dwordx4 v[122:125], v[112:113], off offset:144
	v_ashrrev_i32_e32 v131, 31, v130
	v_lshlrev_b64 v[132:133], 12, v[130:131]
	v_lshl_add_u64 v[142:143], v[130:131], 3, s[0:1]
	v_lshl_add_u64 v[130:131], s[58:59], 0, v[132:133]
	v_lshl_add_u64 v[144:145], v[130:131], 0, v[114:115]
	global_load_dwordx4 v[130:133], v[144:145], off
	s_waitcnt vmcnt(3)
	v_pk_add_f32 v[134:135], v[134:135], v[140:141] op_sel_hi:[1,0] neg_lo:[0,1] neg_hi:[0,1]
	v_pk_add_f32 v[136:137], v[136:137], v[140:141] op_sel_hi:[1,0] neg_lo:[0,1] neg_hi:[0,1]
	v_pk_mul_f32 v[134:135], v[134:135], v[140:141] op_sel:[0,1]
	v_pk_mul_f32 v[136:137], v[136:137], v[140:141] op_sel:[0,1]
	s_waitcnt vmcnt(1)
	v_pk_fma_f32 v[122:123], v[134:135], v[122:123], v[126:127]
	v_pk_fma_f32 v[124:125], v[136:137], v[124:125], v[128:129]
	v_pk_fma_f32 v[122:123], v[122:123], s[14:15], v[148:149] op_sel_hi:[1,0,1]
	v_pk_fma_f32 v[124:125], v[124:125], s[14:15], v[150:151] op_sel_hi:[1,0,1]
	global_store_dwordx4 v[164:165], v[122:125], off offset:144
	global_load_dwordx2 v[140:141], v[142:143], off
	global_load_dwordx4 v[126:129], v[110:111], off
	global_load_dwordx4 v[134:137], v[144:145], off offset:16
	s_waitcnt vmcnt(2)
	v_pk_add_f32 v[130:131], v[130:131], v[140:141] op_sel_hi:[1,0] neg_lo:[0,1] neg_hi:[0,1]
	global_load_dwordx4 v[122:125], v[112:113], off
	v_pk_add_f32 v[132:133], v[132:133], v[140:141] op_sel_hi:[1,0] neg_lo:[0,1] neg_hi:[0,1]
	v_pk_mul_f32 v[130:131], v[130:131], v[140:141] op_sel:[0,1]
	v_pk_mul_f32 v[132:133], v[132:133], v[140:141] op_sel:[0,1]
	s_waitcnt vmcnt(0)
	v_pk_fma_f32 v[122:123], v[130:131], v[122:123], v[126:127]
	v_pk_fma_f32 v[124:125], v[132:133], v[124:125], v[128:129]
	v_pk_fma_f32 v[122:123], v[122:123], s[14:15], v[156:157] op_sel_hi:[1,0,1]
	v_pk_fma_f32 v[124:125], v[124:125], s[14:15], v[158:159] op_sel_hi:[1,0,1]
	global_store_dwordx4 v[144:145], v[122:125], off
	global_load_dwordx2 v[140:141], v[142:143], off
	global_load_dwordx4 v[126:129], v[110:111], off offset:16
	global_load_dwordx4 v[130:133], v[144:145], off offset:128
	s_waitcnt vmcnt(2)
	v_pk_add_f32 v[134:135], v[134:135], v[140:141] op_sel_hi:[1,0] neg_lo:[0,1] neg_hi:[0,1]
	global_load_dwordx4 v[122:125], v[112:113], off offset:16
	v_pk_add_f32 v[136:137], v[136:137], v[140:141] op_sel_hi:[1,0] neg_lo:[0,1] neg_hi:[0,1]
	v_pk_mul_f32 v[134:135], v[134:135], v[140:141] op_sel:[0,1]
	v_pk_mul_f32 v[136:137], v[136:137], v[140:141] op_sel:[0,1]
	s_waitcnt vmcnt(0)
	v_pk_fma_f32 v[122:123], v[134:135], v[122:123], v[126:127]
	v_pk_fma_f32 v[124:125], v[136:137], v[124:125], v[128:129]
	v_pk_fma_f32 v[106:107], v[122:123], s[14:15], v[106:107] op_sel_hi:[1,0,1]
	v_pk_fma_f32 v[108:109], v[124:125], s[14:15], v[108:109] op_sel_hi:[1,0,1]
	global_store_dwordx4 v[144:145], v[106:109], off offset:16
	global_load_dwordx2 v[134:135], v[142:143], off
	global_load_dwordx4 v[122:125], v[110:111], off offset:128
	global_load_dwordx4 v[126:129], v[144:145], off offset:144
	s_waitcnt vmcnt(2)
	v_pk_add_f32 v[130:131], v[130:131], v[134:135] op_sel_hi:[1,0] neg_lo:[0,1] neg_hi:[0,1]
	global_load_dwordx4 v[106:109], v[112:113], off offset:128
	v_pk_add_f32 v[132:133], v[132:133], v[134:135] op_sel_hi:[1,0] neg_lo:[0,1] neg_hi:[0,1]
	v_pk_mul_f32 v[130:131], v[130:131], v[134:135] op_sel:[0,1]
	v_pk_mul_f32 v[132:133], v[132:133], v[134:135] op_sel:[0,1]
	s_waitcnt vmcnt(0)
	v_pk_fma_f32 v[106:107], v[130:131], v[106:107], v[122:123]
	v_pk_fma_f32 v[108:109], v[132:133], v[108:109], v[124:125]
	v_pk_fma_f32 v[102:103], v[106:107], s[14:15], v[102:103] op_sel_hi:[1,0,1]
	v_pk_fma_f32 v[104:105], v[108:109], s[14:15], v[104:105] op_sel_hi:[1,0,1]
	global_store_dwordx4 v[144:145], v[102:105], off offset:128
	global_load_dwordx2 v[130:131], v[142:143], off
	global_load_dwordx4 v[106:109], v[110:111], off offset:144
	v_add_u32_e32 v122, s4, v119
	global_load_dwordx4 v[102:105], v[112:113], off offset:144
	v_ashrrev_i32_e32 v123, 31, v122
	v_lshlrev_b64 v[124:125], 12, v[122:123]
	v_lshl_add_u64 v[132:133], v[122:123], 3, s[0:1]
	v_lshl_add_u64 v[122:123], s[58:59], 0, v[124:125]
	v_lshl_add_u64 v[134:135], v[122:123], 0, v[114:115]
	global_load_dwordx4 v[122:125], v[134:135], off
	s_waitcnt vmcnt(3)
	v_pk_add_f32 v[126:127], v[126:127], v[130:131] op_sel_hi:[1,0] neg_lo:[0,1] neg_hi:[0,1]
	v_pk_add_f32 v[128:129], v[128:129], v[130:131] op_sel_hi:[1,0] neg_lo:[0,1] neg_hi:[0,1]
	v_pk_mul_f32 v[126:127], v[126:127], v[130:131] op_sel:[0,1]
	v_pk_mul_f32 v[128:129], v[128:129], v[130:131] op_sel:[0,1]
	s_waitcnt vmcnt(1)
	v_pk_fma_f32 v[102:103], v[126:127], v[102:103], v[106:107]
	v_pk_fma_f32 v[104:105], v[128:129], v[104:105], v[108:109]
	v_pk_fma_f32 v[98:99], v[102:103], s[14:15], v[98:99] op_sel_hi:[1,0,1]
	v_pk_fma_f32 v[100:101], v[104:105], s[14:15], v[100:101] op_sel_hi:[1,0,1]
	global_store_dwordx4 v[144:145], v[98:101], off offset:144
	global_load_dwordx2 v[126:127], v[132:133], off
	global_load_dwordx4 v[102:105], v[110:111], off
	global_load_dwordx4 v[106:109], v[134:135], off offset:16
	s_waitcnt vmcnt(2)
	v_pk_add_f32 v[122:123], v[122:123], v[126:127] op_sel_hi:[1,0] neg_lo:[0,1] neg_hi:[0,1]
	global_load_dwordx4 v[98:101], v[112:113], off
	v_pk_add_f32 v[124:125], v[124:125], v[126:127] op_sel_hi:[1,0] neg_lo:[0,1] neg_hi:[0,1]
	v_pk_mul_f32 v[122:123], v[122:123], v[126:127] op_sel:[0,1]
	v_pk_mul_f32 v[124:125], v[124:125], v[126:127] op_sel:[0,1]
	s_waitcnt vmcnt(0)
	v_pk_fma_f32 v[98:99], v[122:123], v[98:99], v[102:103]
	v_pk_fma_f32 v[100:101], v[124:125], v[100:101], v[104:105]
	v_pk_fma_f32 v[94:95], v[98:99], s[14:15], v[94:95] op_sel_hi:[1,0,1]
	v_pk_fma_f32 v[96:97], v[100:101], s[14:15], v[96:97] op_sel_hi:[1,0,1]
	global_store_dwordx4 v[134:135], v[94:97], off
	global_load_dwordx2 v[122:123], v[132:133], off
	global_load_dwordx4 v[98:101], v[110:111], off offset:16
	global_load_dwordx4 v[102:105], v[134:135], off offset:128
	s_waitcnt vmcnt(2)
	v_pk_add_f32 v[106:107], v[106:107], v[122:123] op_sel_hi:[1,0] neg_lo:[0,1] neg_hi:[0,1]
	global_load_dwordx4 v[94:97], v[112:113], off offset:16
	v_pk_add_f32 v[108:109], v[108:109], v[122:123] op_sel_hi:[1,0] neg_lo:[0,1] neg_hi:[0,1]
	v_pk_mul_f32 v[106:107], v[106:107], v[122:123] op_sel:[0,1]
	v_pk_mul_f32 v[108:109], v[108:109], v[122:123] op_sel:[0,1]
	s_waitcnt vmcnt(0)
	v_pk_fma_f32 v[94:95], v[106:107], v[94:95], v[98:99]
	v_pk_fma_f32 v[96:97], v[108:109], v[96:97], v[100:101]
	v_pk_fma_f32 v[90:91], v[94:95], s[14:15], v[90:91] op_sel_hi:[1,0,1]
	v_pk_fma_f32 v[92:93], v[96:97], s[14:15], v[92:93] op_sel_hi:[1,0,1]
	global_store_dwordx4 v[134:135], v[90:93], off offset:16
	global_load_dwordx2 v[106:107], v[132:133], off
	global_load_dwordx4 v[94:97], v[110:111], off offset:128
	global_load_dwordx4 v[98:101], v[134:135], off offset:144
	s_waitcnt vmcnt(2)
	v_pk_add_f32 v[102:103], v[102:103], v[106:107] op_sel_hi:[1,0] neg_lo:[0,1] neg_hi:[0,1]
	global_load_dwordx4 v[90:93], v[112:113], off offset:128
	v_pk_add_f32 v[104:105], v[104:105], v[106:107] op_sel_hi:[1,0] neg_lo:[0,1] neg_hi:[0,1]
	v_pk_mul_f32 v[102:103], v[102:103], v[106:107] op_sel:[0,1]
	v_pk_mul_f32 v[104:105], v[104:105], v[106:107] op_sel:[0,1]
	s_waitcnt vmcnt(0)
	v_pk_fma_f32 v[90:91], v[102:103], v[90:91], v[94:95]
	v_pk_fma_f32 v[92:93], v[104:105], v[92:93], v[96:97]
	v_pk_fma_f32 v[86:87], v[90:91], s[14:15], v[86:87] op_sel_hi:[1,0,1]
	v_pk_fma_f32 v[88:89], v[92:93], s[14:15], v[88:89] op_sel_hi:[1,0,1]
	global_store_dwordx4 v[134:135], v[86:89], off offset:128
	global_load_dwordx2 v[102:103], v[132:133], off
	global_load_dwordx4 v[90:93], v[110:111], off offset:144
	v_add_u32_e32 v94, s4, v120
	global_load_dwordx4 v[86:89], v[112:113], off offset:144
	v_ashrrev_i32_e32 v95, 31, v94
	v_lshlrev_b64 v[96:97], 12, v[94:95]
	v_lshl_add_u64 v[104:105], v[94:95], 3, s[0:1]
	v_lshl_add_u64 v[94:95], s[58:59], 0, v[96:97]
	v_lshl_add_u64 v[106:107], v[94:95], 0, v[114:115]
	global_load_dwordx4 v[94:97], v[106:107], off
	s_waitcnt vmcnt(3)
	v_pk_add_f32 v[98:99], v[98:99], v[102:103] op_sel_hi:[1,0] neg_lo:[0,1] neg_hi:[0,1]
	v_pk_add_f32 v[100:101], v[100:101], v[102:103] op_sel_hi:[1,0] neg_lo:[0,1] neg_hi:[0,1]
	v_pk_mul_f32 v[98:99], v[98:99], v[102:103] op_sel:[0,1]
	v_pk_mul_f32 v[100:101], v[100:101], v[102:103] op_sel:[0,1]
	s_waitcnt vmcnt(1)
	v_pk_fma_f32 v[86:87], v[98:99], v[86:87], v[90:91]
	v_pk_fma_f32 v[88:89], v[100:101], v[88:89], v[92:93]
	v_pk_fma_f32 v[82:83], v[86:87], s[14:15], v[82:83] op_sel_hi:[1,0,1]
	v_pk_fma_f32 v[84:85], v[88:89], s[14:15], v[84:85] op_sel_hi:[1,0,1]
	global_store_dwordx4 v[134:135], v[82:85], off offset:144
	global_load_dwordx2 v[98:99], v[104:105], off
	global_load_dwordx4 v[86:89], v[110:111], off
	global_load_dwordx4 v[90:93], v[106:107], off offset:16
	s_waitcnt vmcnt(2)
	v_pk_add_f32 v[94:95], v[94:95], v[98:99] op_sel_hi:[1,0] neg_lo:[0,1] neg_hi:[0,1]
	global_load_dwordx4 v[82:85], v[112:113], off
	v_pk_add_f32 v[96:97], v[96:97], v[98:99] op_sel_hi:[1,0] neg_lo:[0,1] neg_hi:[0,1]
	v_pk_mul_f32 v[94:95], v[94:95], v[98:99] op_sel:[0,1]
	v_pk_mul_f32 v[96:97], v[96:97], v[98:99] op_sel:[0,1]
	s_waitcnt vmcnt(0)
	v_pk_fma_f32 v[82:83], v[94:95], v[82:83], v[86:87]
	v_pk_fma_f32 v[84:85], v[96:97], v[84:85], v[88:89]
	v_pk_fma_f32 v[78:79], v[82:83], s[14:15], v[78:79] op_sel_hi:[1,0,1]
	v_pk_fma_f32 v[80:81], v[84:85], s[14:15], v[80:81] op_sel_hi:[1,0,1]
	global_store_dwordx4 v[106:107], v[78:81], off
	global_load_dwordx2 v[94:95], v[104:105], off
	global_load_dwordx4 v[82:85], v[110:111], off offset:16
	global_load_dwordx4 v[86:89], v[106:107], off offset:128
	s_waitcnt vmcnt(2)
	v_pk_add_f32 v[90:91], v[90:91], v[94:95] op_sel_hi:[1,0] neg_lo:[0,1] neg_hi:[0,1]
	global_load_dwordx4 v[78:81], v[112:113], off offset:16
	v_pk_add_f32 v[92:93], v[92:93], v[94:95] op_sel_hi:[1,0] neg_lo:[0,1] neg_hi:[0,1]
	v_pk_mul_f32 v[90:91], v[90:91], v[94:95] op_sel:[0,1]
	v_pk_mul_f32 v[92:93], v[92:93], v[94:95] op_sel:[0,1]
	s_waitcnt vmcnt(0)
	v_pk_fma_f32 v[78:79], v[90:91], v[78:79], v[82:83]
	v_pk_fma_f32 v[80:81], v[92:93], v[80:81], v[84:85]
	v_pk_fma_f32 v[74:75], v[78:79], s[14:15], v[74:75] op_sel_hi:[1,0,1]
	v_pk_fma_f32 v[76:77], v[80:81], s[14:15], v[76:77] op_sel_hi:[1,0,1]
	global_store_dwordx4 v[106:107], v[74:77], off offset:16
	global_load_dwordx2 v[90:91], v[104:105], off
	global_load_dwordx4 v[78:81], v[110:111], off offset:128
	global_load_dwordx4 v[82:85], v[106:107], off offset:144
	s_waitcnt vmcnt(2)
	v_pk_add_f32 v[86:87], v[86:87], v[90:91] op_sel_hi:[1,0] neg_lo:[0,1] neg_hi:[0,1]
	global_load_dwordx4 v[74:77], v[112:113], off offset:128
	v_pk_add_f32 v[88:89], v[88:89], v[90:91] op_sel_hi:[1,0] neg_lo:[0,1] neg_hi:[0,1]
	v_pk_mul_f32 v[86:87], v[86:87], v[90:91] op_sel:[0,1]
	v_pk_mul_f32 v[88:89], v[88:89], v[90:91] op_sel:[0,1]
	s_waitcnt vmcnt(0)
	v_pk_fma_f32 v[74:75], v[86:87], v[74:75], v[78:79]
	v_pk_fma_f32 v[76:77], v[88:89], v[76:77], v[80:81]
	v_pk_fma_f32 v[66:67], v[74:75], s[14:15], v[66:67] op_sel_hi:[1,0,1]
	v_pk_fma_f32 v[68:69], v[76:77], s[14:15], v[68:69] op_sel_hi:[1,0,1]
	global_store_dwordx4 v[106:107], v[66:69], off offset:128
	global_load_dwordx2 v[78:79], v[104:105], off
	global_load_dwordx4 v[74:77], v[110:111], off offset:144
	s_waitcnt vmcnt(1)
	v_pk_add_f32 v[80:81], v[82:83], v[78:79] op_sel_hi:[1,0] neg_lo:[0,1] neg_hi:[0,1]
	global_load_dwordx4 v[66:69], v[112:113], off offset:144
	v_pk_add_f32 v[82:83], v[84:85], v[78:79] op_sel_hi:[1,0] neg_lo:[0,1] neg_hi:[0,1]
	v_pk_mul_f32 v[80:81], v[80:81], v[78:79] op_sel:[0,1]
	v_pk_mul_f32 v[78:79], v[82:83], v[78:79] op_sel:[0,1]
	s_waitcnt vmcnt(0)
	v_pk_fma_f32 v[66:67], v[80:81], v[66:67], v[74:75]
	v_pk_fma_f32 v[68:69], v[78:79], v[68:69], v[76:77]
	v_pk_fma_f32 v[66:67], v[66:67], s[14:15], v[70:71] op_sel_hi:[1,0,1]
	v_pk_fma_f32 v[68:69], v[68:69], s[14:15], v[72:73] op_sel_hi:[1,0,1]
	global_store_dwordx4 v[106:107], v[66:69], off offset:144
	s_cbranch_scc1 .LBB0_126
	v_mov_b32_e32 v0, v169
	v_mov_b32_e32 v67, v169
	s_movk_i32 s4, 0xb00
	v_lshrrev_b32_e32 v66, 3, v0
	v_lshrrev_b32_e32 v69, 3, v67
	v_add_u32_e32 v66, s9, v66
	v_add_u32_e32 v69, s10, v69
	v_lshlrev_b32_e32 v0, 3, v0
	v_mul_lo_u32 v66, v66, s4
	v_lshlrev_b32_e32 v67, 3, v67
	v_mul_lo_u32 v69, v69, s4
	v_and_or_b32 v0, v0, 56, v66
	v_and_or_b32 v72, v67, 56, v69
	v_add_u32_e32 v66, 0x16000, v0
	v_add_u32_e32 v68, 0x2c000, v0
	v_add_u32_e32 v70, 0x42000, v0
	v_add_u32_e32 v74, 0x16000, v72
	v_add_u32_e32 v76, 0x2c000, v72
	v_add_u32_e32 v78, 0x42000, v72
	s_mov_b64 s[42:43], 0
	s_branch .LBB0_126

.LBB0_136:
	v_mov_b32_e32 v67, v169
	s_mov_b32 s8, s9
	v_lshrrev_b32_e32 v69, 4, v67
	v_ashrrev_i32_e32 v71, 3, v67
	v_lshrrev_b32_e32 v77, 1, v67
	v_and_b32_e32 v80, 4, v69
	v_and_b32_e32 v81, 3, v71
	v_and_b32_e32 v73, 7, v67
	v_xor_b32_e32 v75, v71, v67
	v_and_b32_e32 v77, 16, v77
	v_and_b32_e32 v79, 8, v69
	v_or_b32_e32 v82, v80, v81
	v_lshlrev_b32_e32 v75, 4, v75
	v_or3_b32 v77, v77, v79, v82
	v_bitop3_b32 v79, v80, v73, v81 bitop3:0x36
	v_lshlrev_b32_e32 v71, 7, v71
	v_lshlrev_b32_e32 v79, 4, v79
	v_and_or_b32 v123, v75, s24, v71
	v_lshl_or_b32 v99, v77, 7, v79
	s_waitcnt vmcnt(15)
	ds_write_b128 v123, v[34:37]
	s_waitcnt vmcnt(13)
	ds_write_b128 v99, v[38:41] offset:16384
	s_waitcnt vmcnt(11)
	ds_write_b128 v123, v[42:45] offset:4096
	s_waitcnt vmcnt(9)
	ds_write_b128 v99, v[46:49] offset:20480
	s_waitcnt vmcnt(7)
	ds_write_b128 v123, v[50:53] offset:8192
	s_waitcnt vmcnt(5)
	ds_write_b128 v99, v[54:57] offset:24576
	s_waitcnt vmcnt(3)
	ds_write_b128 v123, v[58:61] offset:12288
	s_waitcnt vmcnt(1)
	ds_write_b128 v99, v[62:65] offset:28672
	v_lshlrev_b32_e32 v35, 7, v67
	v_bfe_u32 v34, v67, 4, 2
	v_and_b32_e32 v36, 0x780, v35
	v_and_b32_e32 v124, 0x2780, v35
	v_bitop3_b32 v35, v69, v73, 3 bitop3:0x6c
	v_mov_b32_e32 v75, v1
	v_lshlrev_b32_e32 v125, 4, v35
	v_lshlrev_b32_e32 v35, 6, v67
	v_bitop3_b32 v34, v34, v73, 4 bitop3:0x36
	v_mov_b32_e32 v73, v1
	v_mov_b32_e32 v67, v1
	v_mov_b32_e32 v69, v1
	v_mov_b32_e32 v77, v1
	v_mov_b32_e32 v71, v1
	v_mov_b32_e32 v79, v1
	v_lshl_add_u64 v[102:103], v[74:75], 1, s[0:1]
	v_mov_b32_e32 v74, 0
	s_mov_b32 s5, s10
	v_and_or_b32 v126, v35, s30, v36
	v_lshlrev_b32_e32 v127, 4, v34
	v_lshl_add_u64 v[100:101], v[72:73], 1, s[0:1]
	v_lshl_add_u64 v[104:105], v[76:77], 1, s[0:1]
	v_lshl_add_u64 v[106:107], v[78:79], 1, s[0:1]
	v_lshlrev_b64 v[108:109], 1, v[0:1]
	v_lshlrev_b64 v[110:111], 1, v[66:67]
	v_lshlrev_b64 v[112:113], 1, v[68:69]
	v_lshlrev_b64 v[114:115], 1, v[70:71]
	s_mov_b32 s9, -2
	s_mov_b64 s[46:47], s[28:29]
	v_mov_b32_e32 v75, v74
	v_mov_b32_e32 v76, v74
	v_mov_b32_e32 v77, v74
	v_mov_b32_e32 v62, v74
	v_mov_b32_e32 v63, v74
	v_mov_b32_e32 v64, v74
	v_mov_b32_e32 v65, v74
	v_mov_b32_e32 v66, v74
	v_mov_b32_e32 v67, v74
	v_mov_b32_e32 v68, v74
	v_mov_b32_e32 v69, v74
	v_mov_b32_e32 v58, v74
	v_mov_b32_e32 v59, v74
	v_mov_b32_e32 v60, v74
	v_mov_b32_e32 v61, v74
	v_mov_b32_e32 v70, v74
	v_mov_b32_e32 v71, v74
	v_mov_b32_e32 v72, v74
	v_mov_b32_e32 v73, v74
	v_mov_b32_e32 v54, v74
	v_mov_b32_e32 v55, v74
	v_mov_b32_e32 v56, v74
	v_mov_b32_e32 v57, v74
	v_mov_b32_e32 v78, v74
	v_mov_b32_e32 v79, v74
	v_mov_b32_e32 v80, v74
	v_mov_b32_e32 v81, v74
	v_mov_b32_e32 v50, v74
	v_mov_b32_e32 v51, v74
	v_mov_b32_e32 v52, v74
	v_mov_b32_e32 v53, v74
	v_mov_b32_e32 v82, v74
	v_mov_b32_e32 v83, v74
	v_mov_b32_e32 v84, v74
	v_mov_b32_e32 v85, v74
	v_mov_b32_e32 v46, v74
	v_mov_b32_e32 v47, v74
	v_mov_b32_e32 v48, v74
	v_mov_b32_e32 v49, v74
	v_mov_b32_e32 v86, v74
	v_mov_b32_e32 v87, v74
	v_mov_b32_e32 v88, v74
	v_mov_b32_e32 v89, v74
	v_mov_b32_e32 v42, v74
	v_mov_b32_e32 v43, v74
	v_mov_b32_e32 v44, v74
	v_mov_b32_e32 v45, v74
	v_mov_b32_e32 v90, v74
	v_mov_b32_e32 v91, v74
	v_mov_b32_e32 v92, v74
	v_mov_b32_e32 v93, v74
	v_mov_b32_e32 v38, v74
	v_mov_b32_e32 v39, v74
	v_mov_b32_e32 v40, v74
	v_mov_b32_e32 v41, v74
	v_mov_b32_e32 v94, v74
	v_mov_b32_e32 v95, v74
	v_mov_b32_e32 v96, v74
	v_mov_b32_e32 v97, v74
	v_mov_b32_e32 v34, v74
	v_mov_b32_e32 v35, v74
	v_mov_b32_e32 v36, v74
	v_mov_b32_e32 v37, v74
	s_waitcnt lgkmcnt(0)
	s_barrier
	v_add_u32_e32 v128, v125, v124
	v_add_u32_e32 v130, v125, v126
	v_add_u32_e32 v129, v127, v126
	v_add_u32_e32 v131, v127, v124
	v_readlane_b32 s100, v255, 36
	s_mul_i32 s100, s100, 0xa0
	s_and_b32 s101, s90, 7
	s_lshl_b32 s101, s101, 2
	s_add_u32 s100, s100, s101
	s_add_u32 s100, s100, 0x1a9d4b80
	s_add_u32 s98, s72, s100
	s_addc_u32 s99, s73, 0
	v_mov_b32_e32 v188, 0x10200
	v_mov_b32_e32 v187, 1
	v_cmp_eq_u32_e32 vcc, 0, v169
	s_mov_b64 s[100:101], exec
	s_and_b64 exec, exec, vcc
	s_cbranch_execz .Ldyn_skip_1
	global_atomic_add v187, v1, v187, s[98:99] sc0

.LBB0_137:
	s_setprio 1
	s_add_u32 s98, s46, s17
	s_addc_u32 s99, s47, 0
	s_add_u32 s100, s46, s16
	s_addc_u32 s101, s47, 0
	ds_read_b32 v189, v188
	ds_read_b128 v[132:135], v128 offset:16384
	ds_read_b128 v[152:155], v128 offset:18432
	ds_read_b128 v[160:163], v128 offset:20480
	ds_read_b128 v[164:167], v128 offset:22528
	ds_read_b128 v[140:143], v130
	ds_read_b128 v[144:147], v130 offset:2048
	ds_read_b128 v[148:151], v130 offset:4096
	ds_read_b128 v[156:159], v130 offset:6144
	s_waitcnt lgkmcnt(3)
	v_mfma_f32_16x16x32_bf16 v[34:37], v[132:135], v[140:143], v[34:37]
	global_load_dwordx4 v[194:197], v108, s[98:99] offset:256
	v_mfma_f32_16x16x32_bf16 v[94:97], v[152:155], v[140:143], v[94:97]
	ds_read_b128 v[198:201], v129
	v_mfma_f32_16x16x32_bf16 v[38:41], v[160:163], v[140:143], v[38:41]
	global_load_dwordx4 v[202:205], v100, s[100:101] offset:256
	v_mfma_f32_16x16x32_bf16 v[90:93], v[164:167], v[140:143], v[90:93]
	ds_read_b128 v[140:143], v129 offset:2048
	s_waitcnt lgkmcnt(4)
	v_mfma_f32_16x16x32_bf16 v[42:45], v[132:135], v[144:147], v[42:45]
	global_load_dwordx4 v[206:209], v110, s[98:99] offset:256
	v_mfma_f32_16x16x32_bf16 v[86:89], v[152:155], v[144:147], v[86:89]
	ds_read_b128 v[210:213], v129 offset:4096
	v_mfma_f32_16x16x32_bf16 v[46:49], v[160:163], v[144:147], v[46:49]
	global_load_dwordx4 v[214:217], v102, s[100:101] offset:256
	v_mfma_f32_16x16x32_bf16 v[82:85], v[164:167], v[144:147], v[82:85]
	ds_read_b128 v[144:147], v129 offset:6144
	s_waitcnt lgkmcnt(5)
	v_mfma_f32_16x16x32_bf16 v[50:53], v[132:135], v[148:151], v[50:53]
	global_load_dwordx4 v[218:221], v112, s[98:99] offset:256
	v_mfma_f32_16x16x32_bf16 v[78:81], v[152:155], v[148:151], v[78:81]
	ds_read_b128 v[222:225], v131 offset:16384
	v_mfma_f32_16x16x32_bf16 v[54:57], v[160:163], v[148:151], v[54:57]
	global_load_dwordx4 v[226:229], v104, s[100:101] offset:256
	v_mfma_f32_16x16x32_bf16 v[70:73], v[164:167], v[148:151], v[70:73]
	ds_read_b128 v[148:151], v131 offset:18432
	s_waitcnt lgkmcnt(6)
	v_mfma_f32_16x16x32_bf16 v[58:61], v[132:135], v[156:159], v[58:61]
	global_load_dwordx4 v[132:135], v114, s[98:99] offset:256
	v_mfma_f32_16x16x32_bf16 v[66:69], v[152:155], v[156:159], v[66:69]
	ds_read_b128 v[152:155], v131 offset:20480
	v_mfma_f32_16x16x32_bf16 v[62:65], v[160:163], v[156:159], v[62:65]
	global_load_dwordx4 v[160:163], v106, s[100:101] offset:256
	v_mfma_f32_16x16x32_bf16 v[74:77], v[164:167], v[156:159], v[74:77]
	ds_read_b128 v[156:159], v131 offset:22528
	s_waitcnt lgkmcnt(3)
	v_mfma_f32_16x16x32_bf16 v[34:37], v[222:225], v[198:201], v[34:37]
	s_waitcnt vmcnt(15)
	ds_write_b128 v123, v[2:5] offset:32768
	s_waitcnt lgkmcnt(3)
	v_mfma_f32_16x16x32_bf16 v[94:97], v[148:151], v[198:201], v[94:97]
	s_waitcnt lgkmcnt(2)
	v_mfma_f32_16x16x32_bf16 v[38:41], v[152:155], v[198:201], v[38:41]
	s_waitcnt vmcnt(14)
	ds_write_b128 v99, v[6:9] offset:49152
	s_waitcnt lgkmcnt(2)
	v_mfma_f32_16x16x32_bf16 v[90:93], v[156:159], v[198:201], v[90:93]
	v_mfma_f32_16x16x32_bf16 v[42:45], v[222:225], v[140:143], v[42:45]
	s_waitcnt vmcnt(13)
	ds_write_b128 v123, v[10:13] offset:36864
	v_mfma_f32_16x16x32_bf16 v[86:89], v[148:151], v[140:143], v[86:89]
	v_mfma_f32_16x16x32_bf16 v[46:49], v[152:155], v[140:143], v[46:49]
	s_waitcnt vmcnt(12)
	ds_write_b128 v99, v[14:17] offset:53248
	v_mfma_f32_16x16x32_bf16 v[82:85], v[156:159], v[140:143], v[82:85]
	v_mfma_f32_16x16x32_bf16 v[50:53], v[222:225], v[210:213], v[50:53]
	s_waitcnt vmcnt(11)
	ds_write_b128 v123, v[18:21] offset:40960
	v_mfma_f32_16x16x32_bf16 v[78:81], v[148:151], v[210:213], v[78:81]
	v_mfma_f32_16x16x32_bf16 v[54:57], v[152:155], v[210:213], v[54:57]
	s_waitcnt vmcnt(10)
	ds_write_b128 v99, v[22:25] offset:57344
	v_mfma_f32_16x16x32_bf16 v[70:73], v[156:159], v[210:213], v[70:73]
	v_mfma_f32_16x16x32_bf16 v[58:61], v[222:225], v[144:147], v[58:61]
	s_waitcnt vmcnt(9)
	ds_write_b128 v123, v[26:29] offset:45056
	v_mfma_f32_16x16x32_bf16 v[66:69], v[148:151], v[144:147], v[66:69]
	v_mfma_f32_16x16x32_bf16 v[62:65], v[152:155], v[144:147], v[62:65]
	s_waitcnt vmcnt(8)
	ds_write_b128 v99, v[30:33] offset:61440
	v_mfma_f32_16x16x32_bf16 v[74:77], v[156:159], v[144:147], v[74:77]
	s_setprio 0
	s_waitcnt lgkmcnt(0)
	s_barrier
	s_setprio 1
	ds_read_b128 v[26:29], v128 offset:49152
	ds_read_b128 v[30:33], v128 offset:51200
	ds_read_b128 v[148:151], v128 offset:53248
	ds_read_b128 v[152:155], v128 offset:55296
	ds_read_b128 v[10:13], v130 offset:32768
	ds_read_b128 v[18:21], v130 offset:34816
	ds_read_b128 v[140:143], v130 offset:36864
	ds_read_b128 v[144:147], v130 offset:38912
	s_waitcnt lgkmcnt(3)
	v_mfma_f32_16x16x32_bf16 v[34:37], v[26:29], v[10:13], v[34:37]
	global_load_dwordx4 v[2:5], v108, s[98:99] offset:384
	v_mfma_f32_16x16x32_bf16 v[94:97], v[30:33], v[10:13], v[94:97]
	ds_read_b128 v[156:159], v129 offset:32768
	v_mfma_f32_16x16x32_bf16 v[38:41], v[148:151], v[10:13], v[38:41]
	global_load_dwordx4 v[6:9], v100, s[100:101] offset:384
	v_mfma_f32_16x16x32_bf16 v[90:93], v[152:155], v[10:13], v[90:93]
	ds_read_b128 v[164:167], v129 offset:34816
	s_waitcnt lgkmcnt(4)
	v_mfma_f32_16x16x32_bf16 v[42:45], v[26:29], v[18:21], v[42:45]
	global_load_dwordx4 v[10:13], v110, s[98:99] offset:384
	v_mfma_f32_16x16x32_bf16 v[86:89], v[30:33], v[18:21], v[86:89]
	ds_read_b128 v[198:201], v129 offset:36864
	v_mfma_f32_16x16x32_bf16 v[46:49], v[148:151], v[18:21], v[46:49]
	global_load_dwordx4 v[14:17], v102, s[100:101] offset:384
	v_mfma_f32_16x16x32_bf16 v[82:85], v[152:155], v[18:21], v[82:85]
	ds_read_b128 v[210:213], v129 offset:38912
	s_waitcnt lgkmcnt(5)
	v_mfma_f32_16x16x32_bf16 v[50:53], v[26:29], v[140:143], v[50:53]
	global_load_dwordx4 v[18:21], v112, s[98:99] offset:384
	v_mfma_f32_16x16x32_bf16 v[78:81], v[30:33], v[140:143], v[78:81]
	ds_read_b128 v[222:225], v131 offset:49152
	v_mfma_f32_16x16x32_bf16 v[54:57], v[148:151], v[140:143], v[54:57]
	global_load_dwordx4 v[22:25], v104, s[100:101] offset:384
	v_mfma_f32_16x16x32_bf16 v[70:73], v[152:155], v[140:143], v[70:73]
	ds_read_b128 v[140:143], v131 offset:51200
	s_waitcnt lgkmcnt(6)
	v_mfma_f32_16x16x32_bf16 v[58:61], v[26:29], v[144:147], v[58:61]
	global_load_dwordx4 v[26:29], v114, s[98:99] offset:384
	v_mfma_f32_16x16x32_bf16 v[66:69], v[30:33], v[144:147], v[66:69]
	ds_read_b128 v[230:233], v131 offset:53248
	v_mfma_f32_16x16x32_bf16 v[62:65], v[148:151], v[144:147], v[62:65]
	global_load_dwordx4 v[30:33], v106, s[100:101] offset:384
	v_mfma_f32_16x16x32_bf16 v[74:77], v[152:155], v[144:147], v[74:77]
	ds_read_b128 v[144:147], v131 offset:55296
	s_waitcnt lgkmcnt(3)
	v_mfma_f32_16x16x32_bf16 v[34:37], v[222:225], v[156:159], v[34:37]
	s_waitcnt vmcnt(15)
	ds_write_b128 v123, v[194:197]
	s_waitcnt lgkmcnt(3)
	v_mfma_f32_16x16x32_bf16 v[94:97], v[140:143], v[156:159], v[94:97]
	s_waitcnt lgkmcnt(2)
	v_mfma_f32_16x16x32_bf16 v[38:41], v[230:233], v[156:159], v[38:41]
	s_waitcnt vmcnt(14)
	ds_write_b128 v99, v[202:205] offset:16384
	s_waitcnt lgkmcnt(2)
	v_mfma_f32_16x16x32_bf16 v[90:93], v[144:147], v[156:159], v[90:93]
	v_mfma_f32_16x16x32_bf16 v[42:45], v[222:225], v[164:167], v[42:45]
	s_waitcnt vmcnt(13)
	ds_write_b128 v123, v[206:209] offset:4096
	v_mfma_f32_16x16x32_bf16 v[86:89], v[140:143], v[164:167], v[86:89]
	v_mfma_f32_16x16x32_bf16 v[46:49], v[230:233], v[164:167], v[46:49]
	s_waitcnt vmcnt(12)
	ds_write_b128 v99, v[214:217] offset:20480
	v_mfma_f32_16x16x32_bf16 v[82:85], v[144:147], v[164:167], v[82:85]
	v_mfma_f32_16x16x32_bf16 v[50:53], v[222:225], v[198:201], v[50:53]
	s_waitcnt vmcnt(11)
	ds_write_b128 v123, v[218:221] offset:8192
	v_mfma_f32_16x16x32_bf16 v[78:81], v[140:143], v[198:201], v[78:81]
	v_mfma_f32_16x16x32_bf16 v[54:57], v[230:233], v[198:201], v[54:57]
	s_waitcnt vmcnt(10)
	ds_write_b128 v99, v[226:229] offset:24576
	v_mfma_f32_16x16x32_bf16 v[70:73], v[144:147], v[198:201], v[70:73]
	v_mfma_f32_16x16x32_bf16 v[58:61], v[222:225], v[210:213], v[58:61]
	s_waitcnt vmcnt(9)
	ds_write_b128 v123, v[132:135] offset:12288
	v_mfma_f32_16x16x32_bf16 v[66:69], v[140:143], v[210:213], v[66:69]
	v_mfma_f32_16x16x32_bf16 v[62:65], v[230:233], v[210:213], v[62:65]
	s_waitcnt vmcnt(8)
	ds_write_b128 v99, v[160:163] offset:28672
	v_mfma_f32_16x16x32_bf16 v[74:77], v[144:147], v[210:213], v[74:77]
	s_mov_b64 exec, vcc
	ds_write_b32 v188, v187
	s_mov_b64 exec, -1
	s_setprio 0
	s_add_i32 s9, s9, 2
	s_add_u32 s46, s46, 0x100
	s_addc_u32 s47, s47, 0
	s_cmp_lt_u32 s9, 12
	s_waitcnt lgkmcnt(0)
	s_barrier
	s_cbranch_scc1 .LBB0_137
	v_readfirstlane_b32 s9, v189
	s_nop 3
	s_add_i32 s9, s9, s2
	s_cmpk_lt_u32 s9, 0x580
	s_cselect_b32 s8, s9, s8
	s_mul_hi_u32 s10, s8, 0xba2e8ba3
	s_lshr_b32 s10, s10, 8
	s_mul_i32 s11, s10, 0x160
	v_mov_b32_e32 v0, v169
	s_sub_i32 s11, s8, s11
	s_lshl_b32 s8, s10, 3
	s_add_i32 s8, s8, s21
	s_and_b32 s10, s11, 7
	v_lshlrev_b32_e32 v100, 3, v0
	v_lshlrev_b32_e32 v0, 7, v0
	s_or_b32 s8, s8, s10
	v_and_b32_e32 v0, 0xfffffc00, v0
	v_lshl_add_u32 v0, s8, 17, v0
	v_and_or_b32 v0, v100, 56, v0
	v_mov_b32_e32 v100, v169
	s_lshl_b32 s10, s11, 4
	s_and_b32 s10, s10, 0x1f80
	v_lshrrev_b32_e32 v101, 3, v100
	v_lshlrev_b32_e32 v100, 3, v100
	v_add_u32_e32 v101, s10, v101
	v_and_b32_e32 v100, 56, v100
	v_lshl_or_b32 v160, v101, 10, v100
	s_cmpk_gt_u32 s9, 0x57f
	v_add_u32_e32 v116, 0x8000, v0
	v_add_u32_e32 v136, 0x10000, v0
	v_add_u32_e32 v174, 0x18000, v0
	v_add_u32_e32 v176, 0x8000, v160
	v_add_u32_e32 v178, 0x10000, v160
	v_add_u32_e32 v180, 0x18000, v160
	s_setprio 1
	ds_read_b128 v[100:103], v128 offset:16384
	ds_read_b128 v[112:115], v128 offset:18432
	ds_read_b128 v[140:143], v128 offset:20480
	ds_read_b128 v[144:147], v128 offset:22528
	ds_read_b128 v[104:107], v130
	ds_read_b128 v[108:111], v130 offset:2048
	ds_read_b128 v[124:127], v130 offset:4096
	ds_read_b128 v[132:135], v130 offset:6144
	v_mov_b32_e32 v161, v1
	v_mov_b32_e32 v117, v1
	v_mov_b32_e32 v177, v1
	v_mov_b32_e32 v137, v1
	v_mov_b32_e32 v179, v1
	v_mov_b32_e32 v175, v1
	v_mov_b32_e32 v181, v1
	v_lshl_add_u64 v[186:187], v[0:1], 1, s[38:39]
	v_lshl_add_u64 v[188:189], v[160:161], 1, s[42:43]
	v_lshl_add_u64 v[116:117], v[116:117], 1, s[38:39]
	v_lshl_add_u64 v[176:177], v[176:177], 1, s[42:43]
	v_lshl_add_u64 v[136:137], v[136:137], 1, s[38:39]
	v_lshl_add_u64 v[178:179], v[178:179], 1, s[42:43]
	v_lshl_add_u64 v[174:175], v[174:175], 1, s[38:39]
	v_lshl_add_u64 v[180:181], v[180:181], 1, s[42:43]
	s_waitcnt lgkmcnt(3)
	v_mfma_f32_16x16x32_bf16 v[148:151], v[100:103], v[104:107], v[34:37]
	s_nop 2
	global_load_dwordx4 v[34:37], v[186:187], off
	v_mfma_f32_16x16x32_bf16 v[94:97], v[112:115], v[104:107], v[94:97]
	ds_read_b128 v[152:155], v129
	v_mfma_f32_16x16x32_bf16 v[156:159], v[140:143], v[104:107], v[38:41]
	s_nop 2
	global_load_dwordx4 v[38:41], v[188:189], off
	v_mfma_f32_16x16x32_bf16 v[90:93], v[144:147], v[104:107], v[90:93]
	ds_read_b128 v[104:107], v129 offset:2048
	s_waitcnt lgkmcnt(4)
	v_mfma_f32_16x16x32_bf16 v[160:163], v[100:103], v[108:111], v[42:45]
	s_nop 2
	global_load_dwordx4 v[42:45], v[116:117], off
	v_mfma_f32_16x16x32_bf16 v[86:89], v[112:115], v[108:111], v[86:89]
	ds_read_b128 v[164:167], v129 offset:4096
	v_mfma_f32_16x16x32_bf16 v[194:197], v[140:143], v[108:111], v[46:49]
	s_nop 2
	global_load_dwordx4 v[46:49], v[176:177], off
	v_mfma_f32_16x16x32_bf16 v[82:85], v[144:147], v[108:111], v[82:85]
	ds_read_b128 v[108:111], v129 offset:6144
	s_waitcnt lgkmcnt(5)
	v_mfma_f32_16x16x32_bf16 v[198:201], v[100:103], v[124:127], v[50:53]
	s_nop 2
	global_load_dwordx4 v[50:53], v[136:137], off
	v_mfma_f32_16x16x32_bf16 v[78:81], v[112:115], v[124:127], v[78:81]
	ds_read_b128 v[202:205], v131 offset:16384
	v_mfma_f32_16x16x32_bf16 v[206:209], v[140:143], v[124:127], v[54:57]
	s_nop 2
	global_load_dwordx4 v[54:57], v[178:179], off
	v_mfma_f32_16x16x32_bf16 v[70:73], v[144:147], v[124:127], v[70:73]
	ds_read_b128 v[124:127], v131 offset:18432
	s_waitcnt lgkmcnt(6)
	v_mfma_f32_16x16x32_bf16 v[100:103], v[100:103], v[132:135], v[58:61]
	s_nop 2
	global_load_dwordx4 v[58:61], v[174:175], off
	v_mfma_f32_16x16x32_bf16 v[66:69], v[112:115], v[132:135], v[66:69]
	ds_read_b128 v[112:115], v131 offset:20480
	v_mfma_f32_16x16x32_bf16 v[140:143], v[140:143], v[132:135], v[62:65]
	s_nop 2
	global_load_dwordx4 v[62:65], v[180:181], off
	v_mfma_f32_16x16x32_bf16 v[74:77], v[144:147], v[132:135], v[74:77]
	ds_read_b128 v[132:135], v131 offset:22528
	s_waitcnt lgkmcnt(3)
	v_mfma_f32_16x16x32_bf16 v[144:147], v[202:205], v[152:155], v[148:151]
	s_waitcnt vmcnt(15)
	ds_write_b128 v123, v[2:5] offset:32768
	s_waitcnt lgkmcnt(3)
	v_mfma_f32_16x16x32_bf16 v[94:97], v[124:127], v[152:155], v[94:97]
	s_waitcnt lgkmcnt(2)
	v_mfma_f32_16x16x32_bf16 v[148:151], v[112:115], v[152:155], v[156:159]
	s_waitcnt vmcnt(14)
	ds_write_b128 v99, v[6:9] offset:49152
	s_waitcnt lgkmcnt(2)
	v_mfma_f32_16x16x32_bf16 v[90:93], v[132:135], v[152:155], v[90:93]
	v_mfma_f32_16x16x32_bf16 v[152:155], v[202:205], v[104:107], v[160:163]
	s_waitcnt vmcnt(13)
	ds_write_b128 v123, v[10:13] offset:36864
	v_mfma_f32_16x16x32_bf16 v[86:89], v[124:127], v[104:107], v[86:89]
	v_mfma_f32_16x16x32_bf16 v[156:159], v[112:115], v[104:107], v[194:197]
	s_waitcnt vmcnt(12)
	ds_write_b128 v99, v[14:17] offset:53248
	v_mfma_f32_16x16x32_bf16 v[82:85], v[132:135], v[104:107], v[82:85]
	v_mfma_f32_16x16x32_bf16 v[104:107], v[202:205], v[164:167], v[198:201]
	s_waitcnt vmcnt(11)
	ds_write_b128 v123, v[18:21] offset:40960
	v_mfma_f32_16x16x32_bf16 v[78:81], v[124:127], v[164:167], v[78:81]
	v_mfma_f32_16x16x32_bf16 v[160:163], v[112:115], v[164:167], v[206:209]
	s_waitcnt vmcnt(10)
	ds_write_b128 v99, v[22:25] offset:57344
	v_mfma_f32_16x16x32_bf16 v[70:73], v[132:135], v[164:167], v[70:73]
	v_mfma_f32_16x16x32_bf16 v[100:103], v[202:205], v[108:111], v[100:103]
	s_waitcnt vmcnt(9)
	ds_write_b128 v123, v[26:29] offset:45056
	v_mfma_f32_16x16x32_bf16 v[66:69], v[124:127], v[108:111], v[66:69]
	v_mfma_f32_16x16x32_bf16 v[112:115], v[112:115], v[108:111], v[140:143]
	s_waitcnt vmcnt(8)
	ds_write_b128 v99, v[30:33] offset:61440
	v_mfma_f32_16x16x32_bf16 v[74:77], v[132:135], v[108:111], v[74:77]
	s_setprio 0
	s_waitcnt lgkmcnt(0)
	s_barrier
	s_setprio 1
	ds_read_b128 v[26:29], v128 offset:49152
	ds_read_b128 v[30:33], v128 offset:51200
	ds_read_b128 v[132:135], v128 offset:53248
	ds_read_b128 v[140:143], v128 offset:55296
	ds_read_b128 v[10:13], v130 offset:32768
	ds_read_b128 v[18:21], v130 offset:34816
	ds_read_b128 v[108:111], v130 offset:36864
	ds_read_b128 v[124:127], v130 offset:38912
	s_waitcnt lgkmcnt(3)
	v_mfma_f32_16x16x32_bf16 v[144:147], v[26:29], v[10:13], v[144:147]
	global_load_dwordx4 v[2:5], v[186:187], off offset:128
	v_mfma_f32_16x16x32_bf16 v[94:97], v[30:33], v[10:13], v[94:97]
	ds_read_b128 v[164:167], v129 offset:32768
	v_mfma_f32_16x16x32_bf16 v[148:151], v[132:135], v[10:13], v[148:151]
	global_load_dwordx4 v[6:9], v[188:189], off offset:128
	v_mfma_f32_16x16x32_bf16 v[90:93], v[140:143], v[10:13], v[90:93]
	ds_read_b128 v[194:197], v129 offset:34816
	s_waitcnt lgkmcnt(4)
	v_mfma_f32_16x16x32_bf16 v[152:155], v[26:29], v[18:21], v[152:155]
	global_load_dwordx4 v[10:13], v[116:117], off offset:128
	v_mfma_f32_16x16x32_bf16 v[86:89], v[30:33], v[18:21], v[86:89]
	ds_read_b128 v[198:201], v129 offset:36864
	v_mfma_f32_16x16x32_bf16 v[156:159], v[132:135], v[18:21], v[156:159]
	global_load_dwordx4 v[14:17], v[176:177], off offset:128
	v_mfma_f32_16x16x32_bf16 v[82:85], v[140:143], v[18:21], v[82:85]
	ds_read_b128 v[202:205], v129 offset:38912
	s_waitcnt lgkmcnt(5)
	v_mfma_f32_16x16x32_bf16 v[104:107], v[26:29], v[108:111], v[104:107]
	global_load_dwordx4 v[18:21], v[136:137], off offset:128
	v_mfma_f32_16x16x32_bf16 v[78:81], v[30:33], v[108:111], v[78:81]
	ds_read_b128 v[206:209], v131 offset:49152
	v_mfma_f32_16x16x32_bf16 v[160:163], v[132:135], v[108:111], v[160:163]
	global_load_dwordx4 v[22:25], v[178:179], off offset:128
	v_mfma_f32_16x16x32_bf16 v[70:73], v[140:143], v[108:111], v[70:73]
	ds_read_b128 v[108:111], v131 offset:51200
	s_waitcnt lgkmcnt(6)
	v_mfma_f32_16x16x32_bf16 v[100:103], v[26:29], v[124:127], v[100:103]
	global_load_dwordx4 v[26:29], v[174:175], off offset:128
	v_mfma_f32_16x16x32_bf16 v[66:69], v[30:33], v[124:127], v[66:69]
	ds_read_b128 v[210:213], v131 offset:53248
	v_mfma_f32_16x16x32_bf16 v[112:115], v[132:135], v[124:127], v[112:115]
	global_load_dwordx4 v[30:33], v[180:181], off offset:128
	v_mfma_f32_16x16x32_bf16 v[124:127], v[140:143], v[124:127], v[74:77]
	ds_read_b128 v[128:131], v131 offset:55296
	s_waitcnt lgkmcnt(3)
	v_mfma_f32_16x16x32_bf16 v[132:135], v[206:209], v[164:167], v[144:147]
	s_waitcnt lgkmcnt(2)
	v_mfma_f32_16x16x32_bf16 v[140:143], v[108:111], v[164:167], v[94:97]
	s_waitcnt lgkmcnt(1)
	v_mfma_f32_16x16x32_bf16 v[144:147], v[210:213], v[164:167], v[148:151]
	s_waitcnt lgkmcnt(0)
	v_mfma_f32_16x16x32_bf16 v[148:151], v[128:131], v[164:167], v[90:93]
	v_mfma_f32_16x16x32_bf16 v[152:155], v[206:209], v[194:197], v[152:155]
	v_mfma_f32_16x16x32_bf16 v[164:167], v[108:111], v[194:197], v[86:89]
	v_mfma_f32_16x16x32_bf16 v[156:159], v[210:213], v[194:197], v[156:159]
	v_mfma_f32_16x16x32_bf16 v[194:197], v[128:131], v[194:197], v[82:85]
	v_mfma_f32_16x16x32_bf16 v[94:97], v[206:209], v[198:201], v[104:107]
	v_mfma_f32_16x16x32_bf16 v[86:89], v[108:111], v[198:201], v[78:81]
	v_mfma_f32_16x16x32_bf16 v[90:93], v[210:213], v[198:201], v[160:163]
	v_mfma_f32_16x16x32_bf16 v[82:85], v[128:131], v[198:201], v[70:73]
	v_mfma_f32_16x16x32_bf16 v[74:77], v[206:209], v[202:205], v[100:103]
	v_mfma_f32_16x16x32_bf16 v[66:69], v[108:111], v[202:205], v[66:69]
	v_mfma_f32_16x16x32_bf16 v[70:73], v[210:213], v[202:205], v[112:115]
	v_mfma_f32_16x16x32_bf16 v[78:81], v[128:131], v[202:205], v[124:127]
	s_setprio 0
	v_mul_f32_e32 v0, 0xbfb8aa3b, v132
	v_exp_f32_e32 v0, v0
	v_mul_f32_e32 v99, 0xbfb8aa3b, v133
	v_exp_f32_e32 v99, v99
	v_mul_f32_e32 v101, 0xbfb8aa3b, v135
	v_add_f32_e32 v0, 1.0, v0
	v_rcp_f32_e32 v100, v0
	v_add_f32_e32 v0, 1.0, v99
	v_mul_f32_e32 v99, 0xbfb8aa3b, v134
	v_exp_f32_e32 v99, v99
	v_exp_f32_e32 v103, v101
	v_rcp_f32_e32 v101, v0
	v_mul_f32_e32 v108, 0xbfb8aa3b, v152
	v_add_f32_e32 v0, 1.0, v99
	v_mul_f32_e32 v99, 0xbfb8aa3b, v140
	v_rcp_f32_e32 v102, v0
	v_add_f32_e32 v0, 1.0, v103
	v_exp_f32_e32 v99, v99
	v_mul_f32_e32 v103, 0xbfb8aa3b, v141
	v_exp_f32_e32 v105, v103
	v_rcp_f32_e32 v103, v0
	v_add_f32_e32 v0, 1.0, v99
	v_mul_f32_e32 v99, 0xbfb8aa3b, v142
	v_rcp_f32_e32 v104, v0
	v_add_f32_e32 v0, 1.0, v105
	v_exp_f32_e32 v99, v99
	v_mul_f32_e32 v105, 0xbfb8aa3b, v143
	v_exp_f32_e32 v107, v105
	v_rcp_f32_e32 v105, v0
	v_add_f32_e32 v0, 1.0, v99
	v_rcp_f32_e32 v106, v0
	v_add_f32_e32 v0, 1.0, v107
	v_rcp_f32_e32 v107, v0
	v_pk_mul_f32 v[100:101], v[132:133], v[100:101]
	v_pk_mul_f32 v[102:103], v[134:135], v[102:103]
	v_pk_mul_f32 v[100:101], v[144:145], v[100:101]
	v_pk_mul_f32 v[102:103], v[146:147], v[102:103]
	v_cvt_pk_bf16_f32 v100, v100, v101
	v_cvt_pk_bf16_f32 v101, v102, v103
	v_pk_mul_f32 v[102:103], v[140:141], v[104:105]
	v_pk_mul_f32 v[104:105], v[142:143], v[106:107]
	v_pk_mul_f32 v[102:103], v[148:149], v[102:103]
	v_pk_mul_f32 v[104:105], v[150:151], v[104:105]
	v_add_u32_e32 v0, s4, v118
	v_cvt_pk_bf16_f32 v102, v102, v103
	v_cvt_pk_bf16_f32 v103, v104, v105
	v_mov_b64_e32 v[104:105], s[44:45]
	v_mad_i64_i32 v[106:107], s[14:15], v0, s20, v[104:105]
	v_or_b32_e32 v0, s5, v119
	v_mul_f32_e32 v109, 0xbfb8aa3b, v153
	v_lshl_add_u64 v[106:107], v[106:107], 0, v[0:1]
	v_mov_b32_e32 v99, v1
	v_exp_f32_e32 v108, v108
	v_exp_f32_e32 v109, v109
	v_lshl_add_u64 v[106:107], v[106:107], 0, v[98:99]
	s_barrier
	global_store_dwordx4 v[106:107], v[100:103], off
	v_mul_f32_e32 v106, 0xbfb8aa3b, v164
	v_mul_f32_e32 v107, 0xbfb8aa3b, v165
	v_mul_f32_e32 v102, 0xbfb8aa3b, v154
	v_mul_f32_e32 v103, 0xbfb8aa3b, v155
	v_exp_f32_e32 v102, v102
	v_exp_f32_e32 v103, v103
	v_add_f32_e32 v100, 1.0, v108
	v_add_f32_e32 v101, 1.0, v109
	v_mul_f32_e32 v108, 0xbfb8aa3b, v166
	v_mul_f32_e32 v109, 0xbfb8aa3b, v167
	v_exp_f32_e32 v106, v106
	v_exp_f32_e32 v107, v107
	v_exp_f32_e32 v108, v108
	v_exp_f32_e32 v109, v109
	v_add_f32_e32 v102, 1.0, v102
	v_add_f32_e32 v103, 1.0, v103
	v_rcp_f32_e32 v100, v100
	v_rcp_f32_e32 v101, v101
	v_rcp_f32_e32 v102, v102
	v_rcp_f32_e32 v103, v103
	v_add_f32_e32 v106, 1.0, v106
	v_add_f32_e32 v107, 1.0, v107
	v_add_f32_e32 v108, 1.0, v108
	v_add_f32_e32 v109, 1.0, v109
	v_rcp_f32_e32 v106, v106
	v_rcp_f32_e32 v107, v107
	v_rcp_f32_e32 v108, v108
	v_rcp_f32_e32 v109, v109
	v_pk_mul_f32 v[100:101], v[152:153], v[100:101]
	v_pk_mul_f32 v[102:103], v[154:155], v[102:103]
	v_pk_mul_f32 v[100:101], v[156:157], v[100:101]
	v_pk_mul_f32 v[102:103], v[158:159], v[102:103]
	v_cvt_pk_bf16_f32 v100, v100, v101
	v_cvt_pk_bf16_f32 v101, v102, v103
	v_pk_mul_f32 v[102:103], v[164:165], v[106:107]
	v_pk_mul_f32 v[106:107], v[166:167], v[108:109]
	v_add_u32_e32 v110, s4, v120
	v_pk_mul_f32 v[102:103], v[194:195], v[102:103]
	v_pk_mul_f32 v[106:107], v[196:197], v[106:107]
	v_cvt_pk_bf16_f32 v102, v102, v103
	v_cvt_pk_bf16_f32 v103, v106, v107
	v_mad_i64_i32 v[106:107], s[14:15], v110, s20, v[104:105]
	v_mul_f32_e32 v108, 0xbfb8aa3b, v94
	v_mul_f32_e32 v109, 0xbfb8aa3b, v95
	v_lshl_add_u64 v[106:107], v[106:107], 0, v[0:1]
	v_exp_f32_e32 v108, v108
	v_exp_f32_e32 v109, v109
	v_lshl_add_u64 v[106:107], v[106:107], 0, v[98:99]
	global_store_dwordx4 v[106:107], v[100:103], off
	v_mul_f32_e32 v106, 0xbfb8aa3b, v86
	v_mul_f32_e32 v107, 0xbfb8aa3b, v87
	v_mul_f32_e32 v102, 0xbfb8aa3b, v96
	v_mul_f32_e32 v103, 0xbfb8aa3b, v97
	v_exp_f32_e32 v102, v102
	v_exp_f32_e32 v103, v103
	v_exp_f32_e32 v106, v106
	v_exp_f32_e32 v107, v107
	v_add_f32_e32 v100, 1.0, v108
	v_add_f32_e32 v101, 1.0, v109
	v_mul_f32_e32 v108, 0xbfb8aa3b, v88
	v_mul_f32_e32 v109, 0xbfb8aa3b, v89
	v_exp_f32_e32 v108, v108
	v_exp_f32_e32 v109, v109
	v_rcp_f32_e32 v100, v100
	v_rcp_f32_e32 v101, v101
	v_add_f32_e32 v102, 1.0, v102
	v_add_f32_e32 v103, 1.0, v103
	v_add_f32_e32 v106, 1.0, v106
	v_add_f32_e32 v107, 1.0, v107
	v_rcp_f32_e32 v102, v102
	v_rcp_f32_e32 v103, v103
	v_rcp_f32_e32 v106, v106
	v_rcp_f32_e32 v107, v107
	v_add_f32_e32 v108, 1.0, v108
	v_add_f32_e32 v109, 1.0, v109
	v_rcp_f32_e32 v108, v108
	v_rcp_f32_e32 v109, v109
	v_pk_mul_f32 v[94:95], v[94:95], v[100:101]
	v_pk_mul_f32 v[86:87], v[86:87], v[106:107]
	v_pk_mul_f32 v[90:91], v[90:91], v[94:95]
	v_pk_mul_f32 v[94:95], v[96:97], v[102:103]
	v_pk_mul_f32 v[82:83], v[82:83], v[86:87]
	v_pk_mul_f32 v[92:93], v[92:93], v[94:95]
	v_cvt_pk_bf16_f32 v90, v90, v91
	v_cvt_pk_bf16_f32 v91, v92, v93
	v_cvt_pk_bf16_f32 v92, v82, v83
	v_pk_mul_f32 v[82:83], v[88:89], v[108:109]
	v_add_u32_e32 v110, s4, v121
	v_pk_mul_f32 v[82:83], v[84:85], v[82:83]
	v_mul_f32_e32 v84, 0xbfb8aa3b, v74
	v_mul_f32_e32 v85, 0xbfb8aa3b, v75
	v_exp_f32_e32 v84, v84
	v_exp_f32_e32 v85, v85
	v_cvt_pk_bf16_f32 v93, v82, v83
	v_mad_i64_i32 v[82:83], s[14:15], v110, s20, v[104:105]
	v_lshl_add_u64 v[82:83], v[82:83], 0, v[0:1]
	v_lshl_add_u64 v[82:83], v[82:83], 0, v[98:99]
	global_store_dwordx4 v[82:83], v[90:93], off
	v_add_f32_e32 v82, 1.0, v84
	v_add_f32_e32 v83, 1.0, v85
	v_mul_f32_e32 v84, 0xbfb8aa3b, v76
	v_mul_f32_e32 v85, 0xbfb8aa3b, v77
	v_mul_f32_e32 v86, 0xbfb8aa3b, v66
	v_mul_f32_e32 v87, 0xbfb8aa3b, v67
	v_exp_f32_e32 v84, v84
	v_exp_f32_e32 v85, v85
	v_exp_f32_e32 v86, v86
	v_exp_f32_e32 v87, v87
	v_mul_f32_e32 v88, 0xbfb8aa3b, v68
	v_mul_f32_e32 v89, 0xbfb8aa3b, v69
	v_exp_f32_e32 v88, v88
	v_exp_f32_e32 v89, v89
	v_rcp_f32_e32 v82, v82
	v_rcp_f32_e32 v83, v83
	v_add_f32_e32 v84, 1.0, v84
	v_add_f32_e32 v85, 1.0, v85
	v_add_f32_e32 v86, 1.0, v86
	v_add_f32_e32 v87, 1.0, v87
	v_rcp_f32_e32 v84, v84
	v_rcp_f32_e32 v85, v85
	v_rcp_f32_e32 v86, v86
	v_rcp_f32_e32 v87, v87
	v_add_f32_e32 v88, 1.0, v88
	v_add_f32_e32 v89, 1.0, v89
	v_rcp_f32_e32 v88, v88
	v_rcp_f32_e32 v89, v89
	v_pk_mul_f32 v[74:75], v[74:75], v[82:83]
	v_pk_mul_f32 v[66:67], v[66:67], v[86:87]
	v_pk_mul_f32 v[70:71], v[70:71], v[74:75]
	v_pk_mul_f32 v[74:75], v[76:77], v[84:85]
	v_pk_mul_f32 v[66:67], v[78:79], v[66:67]
	v_pk_mul_f32 v[72:73], v[72:73], v[74:75]
	v_cvt_pk_bf16_f32 v70, v70, v71
	v_cvt_pk_bf16_f32 v71, v72, v73
	v_cvt_pk_bf16_f32 v72, v66, v67
	v_pk_mul_f32 v[66:67], v[68:69], v[88:89]
	v_add_u32_e32 v90, s4, v122
	v_pk_mul_f32 v[66:67], v[80:81], v[66:67]
	s_nop 0
	v_cvt_pk_bf16_f32 v73, v66, v67
	v_mad_i64_i32 v[66:67], s[4:5], v90, s20, v[104:105]
	v_lshl_add_u64 v[66:67], v[66:67], 0, v[0:1]
	v_lshl_add_u64 v[66:67], v[66:67], 0, v[98:99]
	global_store_dwordx4 v[66:67], v[70:73], off
	s_cbranch_scc0 .LBB0_135

.LBB0_156:
	v_mov_b32_e32 v67, v169
	s_mov_b32 s11, s5
	v_lshrrev_b32_e32 v69, 4, v67
	v_ashrrev_i32_e32 v71, 3, v67
	v_lshrrev_b32_e32 v77, 1, v67
	v_and_b32_e32 v80, 4, v69
	v_and_b32_e32 v81, 3, v71
	v_and_b32_e32 v73, 7, v67
	v_xor_b32_e32 v75, v71, v67
	v_and_b32_e32 v77, 16, v77
	v_and_b32_e32 v79, 8, v69
	v_or_b32_e32 v82, v80, v81
	v_lshlrev_b32_e32 v75, 4, v75
	v_or3_b32 v77, v77, v79, v82
	v_bitop3_b32 v79, v80, v73, v81 bitop3:0x36
	v_lshlrev_b32_e32 v71, 7, v71
	v_lshlrev_b32_e32 v79, 4, v79
	v_and_or_b32 v117, v75, s24, v71
	v_lshl_or_b32 v116, v77, 7, v79
	s_waitcnt vmcnt(15)
	ds_write_b128 v117, v[34:37]
	s_waitcnt vmcnt(13)
	ds_write_b128 v116, v[38:41] offset:16384
	s_waitcnt vmcnt(11)
	ds_write_b128 v117, v[42:45] offset:4096
	s_waitcnt vmcnt(9)
	ds_write_b128 v116, v[46:49] offset:20480
	s_waitcnt vmcnt(7)
	ds_write_b128 v117, v[50:53] offset:8192
	s_waitcnt vmcnt(5)
	ds_write_b128 v116, v[54:57] offset:24576
	s_waitcnt vmcnt(3)
	ds_write_b128 v117, v[58:61] offset:12288
	s_waitcnt vmcnt(1)
	ds_write_b128 v116, v[62:65] offset:28672
	v_lshlrev_b32_e32 v34, 7, v67
	v_and_b32_e32 v35, 0x780, v34
	v_and_b32_e32 v118, 0x2780, v34
	v_bitop3_b32 v34, v69, v73, 3 bitop3:0x6c
	v_bfe_u32 v77, v67, 4, 2
	v_lshlrev_b32_e32 v119, 4, v34
	v_lshlrev_b32_e32 v34, 6, v67
	v_mov_b32_e32 v75, v1
	v_and_or_b32 v120, v34, s30, v35
	v_bitop3_b32 v34, v77, v73, 4 bitop3:0x36
	v_mov_b32_e32 v73, v1
	v_mov_b32_e32 v67, v1
	v_mov_b32_e32 v69, v1
	v_mov_b32_e32 v77, v1
	v_mov_b32_e32 v71, v1
	v_mov_b32_e32 v79, v1
	v_lshl_add_u64 v[100:101], v[74:75], 1, s[28:29]
	v_mov_b32_e32 v74, 0
	s_mov_b32 s10, s9
	s_mov_b32 s4, s8
	v_lshlrev_b32_e32 v121, 4, v34
	v_lshl_add_u64 v[98:99], v[72:73], 1, s[28:29]
	v_lshl_add_u64 v[102:103], v[76:77], 1, s[28:29]
	v_lshl_add_u64 v[104:105], v[78:79], 1, s[28:29]
	v_lshlrev_b64 v[106:107], 1, v[0:1]
	v_lshlrev_b64 v[108:109], 1, v[66:67]
	v_lshlrev_b64 v[110:111], 1, v[68:69]
	v_lshlrev_b64 v[112:113], 1, v[70:71]
	s_mov_b32 s5, -2
	s_mov_b64 s[38:39], s[72:73]
	v_mov_b32_e32 v75, v74
	v_mov_b32_e32 v76, v74
	v_mov_b32_e32 v77, v74
	v_mov_b32_e32 v62, v74
	v_mov_b32_e32 v63, v74
	v_mov_b32_e32 v64, v74
	v_mov_b32_e32 v65, v74
	v_mov_b32_e32 v66, v74
	v_mov_b32_e32 v67, v74
	v_mov_b32_e32 v68, v74
	v_mov_b32_e32 v69, v74
	v_mov_b32_e32 v58, v74
	v_mov_b32_e32 v59, v74
	v_mov_b32_e32 v60, v74
	v_mov_b32_e32 v61, v74
	v_mov_b32_e32 v70, v74
	v_mov_b32_e32 v71, v74
	v_mov_b32_e32 v72, v74
	v_mov_b32_e32 v73, v74
	v_mov_b32_e32 v54, v74
	v_mov_b32_e32 v55, v74
	v_mov_b32_e32 v56, v74
	v_mov_b32_e32 v57, v74
	v_mov_b32_e32 v78, v74
	v_mov_b32_e32 v79, v74
	v_mov_b32_e32 v80, v74
	v_mov_b32_e32 v81, v74
	v_mov_b32_e32 v50, v74
	v_mov_b32_e32 v51, v74
	v_mov_b32_e32 v52, v74
	v_mov_b32_e32 v53, v74
	v_mov_b32_e32 v82, v74
	v_mov_b32_e32 v83, v74
	v_mov_b32_e32 v84, v74
	v_mov_b32_e32 v85, v74
	v_mov_b32_e32 v46, v74
	v_mov_b32_e32 v47, v74
	v_mov_b32_e32 v48, v74
	v_mov_b32_e32 v49, v74
	v_mov_b32_e32 v86, v74
	v_mov_b32_e32 v87, v74
	v_mov_b32_e32 v88, v74
	v_mov_b32_e32 v89, v74
	v_mov_b32_e32 v42, v74
	v_mov_b32_e32 v43, v74
	v_mov_b32_e32 v44, v74
	v_mov_b32_e32 v45, v74
	v_mov_b32_e32 v90, v74
	v_mov_b32_e32 v91, v74
	v_mov_b32_e32 v92, v74
	v_mov_b32_e32 v93, v74
	v_mov_b32_e32 v38, v74
	v_mov_b32_e32 v39, v74
	v_mov_b32_e32 v40, v74
	v_mov_b32_e32 v41, v74
	v_mov_b32_e32 v94, v74
	v_mov_b32_e32 v95, v74
	v_mov_b32_e32 v96, v74
	v_mov_b32_e32 v97, v74
	v_mov_b32_e32 v34, v74
	v_mov_b32_e32 v35, v74
	v_mov_b32_e32 v36, v74
	v_mov_b32_e32 v37, v74
	s_waitcnt lgkmcnt(0)
	s_barrier
	v_readlane_b32 s100, v255, 36
	s_mul_i32 s100, s100, 0xa0
	s_and_b32 s101, s90, 7
	s_lshl_b32 s101, s101, 2
	s_add_u32 s100, s100, s101
	s_add_u32 s100, s100, 0x1a9d4ba0
	s_add_u32 s98, s72, s100
	s_addc_u32 s99, s73, 0
	v_mov_b32_e32 v186, 0x10200
	v_mov_b32_e32 v181, 1
	v_cmp_eq_u32_e32 vcc, 0, v169
	s_mov_b64 s[100:101], exec
	s_and_b64 exec, exec, vcc
	s_cbranch_execz .Ldyn_skip_2
	global_atomic_add v181, v1, v181, s[98:99] sc0

.LBB0_157:
	s_setprio 1
	s_add_u32 s98, s38, s31
	s_addc_u32 s99, s39, 0
	s_add_u32 s100, s38, s36
	s_addc_u32 s101, s39, 0
	v_add_u32_e32 v122, v119, v118
	v_add_u32_e32 v124, v119, v120
	v_add_u32_e32 v123, v121, v120
	ds_read_b32 v187, v186
	ds_read_b128 v[126:129], v122 offset:16384
	ds_read_b128 v[144:147], v122 offset:18432
	ds_read_b128 v[158:161], v122 offset:20480
	ds_read_b128 v[162:165], v122 offset:22528
	ds_read_b128 v[130:133], v124
	ds_read_b128 v[134:137], v124 offset:2048
	ds_read_b128 v[140:143], v124 offset:4096
	ds_read_b128 v[148:151], v124 offset:6144
	s_waitcnt lgkmcnt(3)
	v_mfma_f32_16x16x32_bf16 v[34:37], v[126:129], v[130:133], v[34:37]
	global_load_dwordx4 v[194:197], v106, s[98:99] offset:256
	v_mfma_f32_16x16x32_bf16 v[94:97], v[144:147], v[130:133], v[94:97]
	ds_read_b128 v[198:201], v123
	v_mfma_f32_16x16x32_bf16 v[38:41], v[158:161], v[130:133], v[38:41]
	global_load_dwordx4 v[202:205], v98, s[100:101] offset:256
	v_mfma_f32_16x16x32_bf16 v[90:93], v[162:165], v[130:133], v[90:93]
	ds_read_b128 v[206:209], v123 offset:2048
	s_waitcnt lgkmcnt(4)
	v_mfma_f32_16x16x32_bf16 v[42:45], v[126:129], v[134:137], v[42:45]
	global_load_dwordx4 v[210:213], v108, s[98:99] offset:256
	v_mfma_f32_16x16x32_bf16 v[86:89], v[144:147], v[134:137], v[86:89]
	ds_read_b128 v[214:217], v123 offset:4096
	v_mfma_f32_16x16x32_bf16 v[46:49], v[158:161], v[134:137], v[46:49]
	global_load_dwordx4 v[218:221], v100, s[100:101] offset:256
	v_mfma_f32_16x16x32_bf16 v[82:85], v[162:165], v[134:137], v[82:85]
	v_add_u32_e32 v130, v121, v118
	ds_read_b128 v[132:135], v123 offset:6144
	s_waitcnt lgkmcnt(5)
	v_mfma_f32_16x16x32_bf16 v[50:53], v[126:129], v[140:143], v[50:53]
	global_load_dwordx4 v[222:225], v110, s[98:99] offset:256
	v_mfma_f32_16x16x32_bf16 v[78:81], v[144:147], v[140:143], v[78:81]
	ds_read_b128 v[226:229], v130 offset:16384
	v_mfma_f32_16x16x32_bf16 v[54:57], v[158:161], v[140:143], v[54:57]
	global_load_dwordx4 v[230:233], v102, s[100:101] offset:256
	v_mfma_f32_16x16x32_bf16 v[70:73], v[162:165], v[140:143], v[70:73]
	ds_read_b128 v[140:143], v130 offset:18432
	s_waitcnt lgkmcnt(6)
	v_mfma_f32_16x16x32_bf16 v[58:61], v[126:129], v[148:151], v[58:61]
	global_load_dwordx4 v[126:129], v112, s[98:99] offset:256
	v_mfma_f32_16x16x32_bf16 v[66:69], v[144:147], v[148:151], v[66:69]
	ds_read_b128 v[144:147], v130 offset:20480
	v_mfma_f32_16x16x32_bf16 v[62:65], v[158:161], v[148:151], v[62:65]
	global_load_dwordx4 v[158:161], v104, s[100:101] offset:256
	v_mfma_f32_16x16x32_bf16 v[74:77], v[162:165], v[148:151], v[74:77]
	ds_read_b128 v[148:151], v130 offset:22528
	s_waitcnt lgkmcnt(3)
	v_mfma_f32_16x16x32_bf16 v[34:37], v[226:229], v[198:201], v[34:37]
	s_waitcnt vmcnt(15)
	ds_write_b128 v117, v[2:5] offset:32768
	s_waitcnt lgkmcnt(3)
	v_mfma_f32_16x16x32_bf16 v[94:97], v[140:143], v[198:201], v[94:97]
	s_waitcnt lgkmcnt(2)
	v_mfma_f32_16x16x32_bf16 v[38:41], v[144:147], v[198:201], v[38:41]
	s_waitcnt vmcnt(14)
	ds_write_b128 v116, v[6:9] offset:49152
	s_waitcnt lgkmcnt(2)
	v_mfma_f32_16x16x32_bf16 v[90:93], v[148:151], v[198:201], v[90:93]
	v_mfma_f32_16x16x32_bf16 v[42:45], v[226:229], v[206:209], v[42:45]
	s_waitcnt vmcnt(13)
	ds_write_b128 v117, v[10:13] offset:36864
	v_mfma_f32_16x16x32_bf16 v[86:89], v[140:143], v[206:209], v[86:89]
	v_mfma_f32_16x16x32_bf16 v[46:49], v[144:147], v[206:209], v[46:49]
	s_waitcnt vmcnt(12)
	ds_write_b128 v116, v[14:17] offset:53248
	v_mfma_f32_16x16x32_bf16 v[82:85], v[148:151], v[206:209], v[82:85]
	v_mfma_f32_16x16x32_bf16 v[50:53], v[226:229], v[214:217], v[50:53]
	s_waitcnt vmcnt(11)
	ds_write_b128 v117, v[18:21] offset:40960
	v_mfma_f32_16x16x32_bf16 v[78:81], v[140:143], v[214:217], v[78:81]
	v_mfma_f32_16x16x32_bf16 v[54:57], v[144:147], v[214:217], v[54:57]
	s_waitcnt vmcnt(10)
	ds_write_b128 v116, v[22:25] offset:57344
	v_mfma_f32_16x16x32_bf16 v[70:73], v[148:151], v[214:217], v[70:73]
	v_mfma_f32_16x16x32_bf16 v[58:61], v[226:229], v[132:135], v[58:61]
	s_waitcnt vmcnt(9)
	ds_write_b128 v117, v[26:29] offset:45056
	v_mfma_f32_16x16x32_bf16 v[66:69], v[140:143], v[132:135], v[66:69]
	v_mfma_f32_16x16x32_bf16 v[62:65], v[144:147], v[132:135], v[62:65]
	s_waitcnt vmcnt(8)
	ds_write_b128 v116, v[30:33] offset:61440
	v_mfma_f32_16x16x32_bf16 v[74:77], v[148:151], v[132:135], v[74:77]
	s_setprio 0
	s_waitcnt lgkmcnt(0)
	s_barrier
	s_setprio 1
	ds_read_b128 v[26:29], v122 offset:49152
	ds_read_b128 v[30:33], v122 offset:51200
	ds_read_b128 v[144:147], v122 offset:53248
	ds_read_b128 v[148:151], v122 offset:55296
	ds_read_b128 v[10:13], v124 offset:32768
	ds_read_b128 v[18:21], v124 offset:34816
	ds_read_b128 v[132:135], v124 offset:36864
	ds_read_b128 v[140:143], v124 offset:38912
	s_waitcnt lgkmcnt(3)
	v_mfma_f32_16x16x32_bf16 v[34:37], v[26:29], v[10:13], v[34:37]
	global_load_dwordx4 v[2:5], v106, s[98:99] offset:384
	v_mfma_f32_16x16x32_bf16 v[94:97], v[30:33], v[10:13], v[94:97]
	ds_read_b128 v[162:165], v123 offset:32768
	v_mfma_f32_16x16x32_bf16 v[38:41], v[144:147], v[10:13], v[38:41]
	global_load_dwordx4 v[6:9], v98, s[100:101] offset:384
	v_mfma_f32_16x16x32_bf16 v[90:93], v[148:151], v[10:13], v[90:93]
	ds_read_b128 v[198:201], v123 offset:34816
	s_waitcnt lgkmcnt(4)
	v_mfma_f32_16x16x32_bf16 v[42:45], v[26:29], v[18:21], v[42:45]
	global_load_dwordx4 v[10:13], v108, s[98:99] offset:384
	v_mfma_f32_16x16x32_bf16 v[86:89], v[30:33], v[18:21], v[86:89]
	ds_read_b128 v[206:209], v123 offset:36864
	v_mfma_f32_16x16x32_bf16 v[46:49], v[144:147], v[18:21], v[46:49]
	global_load_dwordx4 v[14:17], v100, s[100:101] offset:384
	v_mfma_f32_16x16x32_bf16 v[82:85], v[148:151], v[18:21], v[82:85]
	ds_read_b128 v[214:217], v123 offset:38912
	s_waitcnt lgkmcnt(5)
	v_mfma_f32_16x16x32_bf16 v[50:53], v[26:29], v[132:135], v[50:53]
	global_load_dwordx4 v[18:21], v110, s[98:99] offset:384
	v_mfma_f32_16x16x32_bf16 v[78:81], v[30:33], v[132:135], v[78:81]
	ds_read_b128 v[226:229], v130 offset:49152
	v_mfma_f32_16x16x32_bf16 v[54:57], v[144:147], v[132:135], v[54:57]
	global_load_dwordx4 v[22:25], v102, s[100:101] offset:384
	v_mfma_f32_16x16x32_bf16 v[70:73], v[148:151], v[132:135], v[70:73]
	ds_read_b128 v[132:135], v130 offset:51200
	s_waitcnt lgkmcnt(6)
	v_mfma_f32_16x16x32_bf16 v[58:61], v[26:29], v[140:143], v[58:61]
	global_load_dwordx4 v[26:29], v112, s[98:99] offset:384
	v_mfma_f32_16x16x32_bf16 v[66:69], v[30:33], v[140:143], v[66:69]
	ds_read_b128 v[234:237], v130 offset:53248
	v_mfma_f32_16x16x32_bf16 v[62:65], v[144:147], v[140:143], v[62:65]
	global_load_dwordx4 v[30:33], v104, s[100:101] offset:384
	v_mfma_f32_16x16x32_bf16 v[74:77], v[148:151], v[140:143], v[74:77]
	ds_read_b128 v[140:143], v130 offset:55296
	s_waitcnt lgkmcnt(3)
	v_mfma_f32_16x16x32_bf16 v[34:37], v[226:229], v[162:165], v[34:37]
	s_waitcnt vmcnt(15)
	ds_write_b128 v117, v[194:197]
	s_waitcnt lgkmcnt(3)
	v_mfma_f32_16x16x32_bf16 v[94:97], v[132:135], v[162:165], v[94:97]
	s_waitcnt lgkmcnt(2)
	v_mfma_f32_16x16x32_bf16 v[38:41], v[234:237], v[162:165], v[38:41]
	s_waitcnt vmcnt(14)
	ds_write_b128 v116, v[202:205] offset:16384
	s_waitcnt lgkmcnt(2)
	v_mfma_f32_16x16x32_bf16 v[90:93], v[140:143], v[162:165], v[90:93]
	v_mfma_f32_16x16x32_bf16 v[42:45], v[226:229], v[198:201], v[42:45]
	s_waitcnt vmcnt(13)
	ds_write_b128 v117, v[210:213] offset:4096
	v_mfma_f32_16x16x32_bf16 v[86:89], v[132:135], v[198:201], v[86:89]
	v_mfma_f32_16x16x32_bf16 v[46:49], v[234:237], v[198:201], v[46:49]
	s_waitcnt vmcnt(12)
	ds_write_b128 v116, v[218:221] offset:20480
	v_mfma_f32_16x16x32_bf16 v[82:85], v[140:143], v[198:201], v[82:85]
	v_mfma_f32_16x16x32_bf16 v[50:53], v[226:229], v[206:209], v[50:53]
	s_waitcnt vmcnt(11)
	ds_write_b128 v117, v[222:225] offset:8192
	v_mfma_f32_16x16x32_bf16 v[78:81], v[132:135], v[206:209], v[78:81]
	v_mfma_f32_16x16x32_bf16 v[54:57], v[234:237], v[206:209], v[54:57]
	s_waitcnt vmcnt(10)
	ds_write_b128 v116, v[230:233] offset:24576
	v_mfma_f32_16x16x32_bf16 v[70:73], v[140:143], v[206:209], v[70:73]
	v_mfma_f32_16x16x32_bf16 v[58:61], v[226:229], v[214:217], v[58:61]
	s_waitcnt vmcnt(9)
	ds_write_b128 v117, v[126:129] offset:12288
	v_mfma_f32_16x16x32_bf16 v[66:69], v[132:135], v[214:217], v[66:69]
	v_mfma_f32_16x16x32_bf16 v[62:65], v[234:237], v[214:217], v[62:65]
	s_waitcnt vmcnt(8)
	ds_write_b128 v116, v[158:161] offset:28672
	v_mfma_f32_16x16x32_bf16 v[74:77], v[140:143], v[214:217], v[74:77]
	s_mov_b64 exec, vcc
	ds_write_b32 v186, v181
	s_mov_b64 exec, -1
	s_setprio 0
	s_add_i32 s5, s5, 2
	s_add_u32 s38, s38, 0x100
	s_addc_u32 s39, s39, 0
	s_cmp_lt_u32 s5, 12
	s_waitcnt lgkmcnt(0)
	s_barrier
	s_cbranch_scc1 .LBB0_157
	v_readfirstlane_b32 s5, v187
	s_nop 3
	s_add_i32 s5, s5, s2
	s_cmpk_lt_u32 s5, 0x100
	s_cselect_b64 s[44:45], -1, 0
	s_and_b64 s[8:9], s[44:45], exec
	s_cselect_b32 s9, s5, s11
	s_lshr_b32 s8, s9, 3
	s_and_b32 s8, s8, 0x1fffff8
	s_add_i32 s8, s8, s21
	s_and_b32 s11, s9, 7
	v_mov_b32_e32 v0, v169
	s_or_b32 s8, s8, s11
	s_lshl_b32 s8, s8, 7
	v_lshrrev_b32_e32 v98, 3, v0
	v_lshlrev_b32_e32 v0, 3, v0
	v_add_u32_e32 v98, s8, v98
	v_and_b32_e32 v0, 56, v0
	v_lshl_or_b32 v0, v98, 10, v0
	v_mov_b32_e32 v98, v169
	s_lshl_b32 s9, s9, 4
	s_and_b32 s9, s9, 0x380
	v_lshrrev_b32_e32 v99, 3, v98
	v_lshlrev_b32_e32 v98, 3, v98
	v_add_u32_e32 v99, s9, v99
	v_and_b32_e32 v98, 56, v98
	v_add_u32_e32 v114, 0x8000, v0
	v_add_u32_e32 v136, 0x10000, v0
	v_lshl_or_b32 v162, v99, 10, v98
	v_add_u32_e32 v166, 0x18000, v0
	v_add_u32_e32 v174, 0x8000, v162
	v_add_u32_e32 v176, 0x10000, v162
	v_add_u32_e32 v178, 0x18000, v162
	s_setprio 1
	ds_read_b128 v[98:101], v122 offset:16384
	ds_read_b128 v[110:113], v122 offset:18432
	ds_read_b128 v[132:135], v122 offset:20480
	ds_read_b128 v[140:143], v122 offset:22528
	ds_read_b128 v[102:105], v124
	ds_read_b128 v[106:109], v124 offset:2048
	ds_read_b128 v[118:121], v124 offset:4096
	ds_read_b128 v[126:129], v124 offset:6144
	v_readlane_b32 s14, v254, 45
	v_readlane_b32 s15, v254, 46
	v_mov_b32_e32 v163, v1
	v_mov_b32_e32 v115, v1
	v_mov_b32_e32 v175, v1
	v_mov_b32_e32 v137, v1
	v_mov_b32_e32 v177, v1
	v_mov_b32_e32 v167, v1
	v_mov_b32_e32 v179, v1
	v_lshl_add_u64 v[180:181], v[0:1], 1, s[14:15]
	v_lshl_add_u64 v[186:187], v[162:163], 1, s[34:35]
	v_lshl_add_u64 v[188:189], v[114:115], 1, s[14:15]
	v_lshl_add_u64 v[174:175], v[174:175], 1, s[34:35]
	v_lshl_add_u64 v[136:137], v[136:137], 1, s[14:15]
	v_lshl_add_u64 v[176:177], v[176:177], 1, s[34:35]
	v_lshl_add_u64 v[166:167], v[166:167], 1, s[14:15]
	v_lshl_add_u64 v[178:179], v[178:179], 1, s[34:35]
	s_waitcnt lgkmcnt(3)
	v_mfma_f32_16x16x32_bf16 v[144:147], v[98:101], v[102:105], v[34:37]
	s_nop 2
	global_load_dwordx4 v[34:37], v[180:181], off
	v_mfma_f32_16x16x32_bf16 v[94:97], v[110:113], v[102:105], v[94:97]
	ds_read_b128 v[148:151], v123
	v_mfma_f32_16x16x32_bf16 v[158:161], v[132:135], v[102:105], v[38:41]
	s_nop 2
	global_load_dwordx4 v[38:41], v[186:187], off
	v_mfma_f32_16x16x32_bf16 v[90:93], v[140:143], v[102:105], v[90:93]
	ds_read_b128 v[102:105], v123 offset:2048
	s_waitcnt lgkmcnt(4)
	v_mfma_f32_16x16x32_bf16 v[162:165], v[98:101], v[106:109], v[42:45]
	s_nop 2
	global_load_dwordx4 v[42:45], v[188:189], off
	v_mfma_f32_16x16x32_bf16 v[86:89], v[110:113], v[106:109], v[86:89]
	ds_read_b128 v[194:197], v123 offset:4096
	v_mfma_f32_16x16x32_bf16 v[198:201], v[132:135], v[106:109], v[46:49]
	s_nop 2
	global_load_dwordx4 v[46:49], v[174:175], off
	v_mfma_f32_16x16x32_bf16 v[82:85], v[140:143], v[106:109], v[82:85]
	ds_read_b128 v[106:109], v123 offset:6144
	s_waitcnt lgkmcnt(5)
	v_mfma_f32_16x16x32_bf16 v[202:205], v[98:101], v[118:121], v[50:53]
	s_nop 2
	global_load_dwordx4 v[50:53], v[136:137], off
	v_mfma_f32_16x16x32_bf16 v[78:81], v[110:113], v[118:121], v[78:81]
	ds_read_b128 v[206:209], v130 offset:16384
	v_mfma_f32_16x16x32_bf16 v[210:213], v[132:135], v[118:121], v[54:57]
	s_nop 2
	global_load_dwordx4 v[54:57], v[176:177], off
	v_mfma_f32_16x16x32_bf16 v[70:73], v[140:143], v[118:121], v[70:73]
	ds_read_b128 v[118:121], v130 offset:18432
	s_waitcnt lgkmcnt(6)
	v_mfma_f32_16x16x32_bf16 v[98:101], v[98:101], v[126:129], v[58:61]
	s_nop 2
	global_load_dwordx4 v[58:61], v[166:167], off
	v_mfma_f32_16x16x32_bf16 v[66:69], v[110:113], v[126:129], v[66:69]
	ds_read_b128 v[110:113], v130 offset:20480
	v_mfma_f32_16x16x32_bf16 v[132:135], v[132:135], v[126:129], v[62:65]
	s_nop 2
	global_load_dwordx4 v[62:65], v[178:179], off
	v_mfma_f32_16x16x32_bf16 v[74:77], v[140:143], v[126:129], v[74:77]
	ds_read_b128 v[126:129], v130 offset:22528
	s_waitcnt lgkmcnt(3)
	v_mfma_f32_16x16x32_bf16 v[140:143], v[206:209], v[148:151], v[144:147]
	s_waitcnt vmcnt(15)
	ds_write_b128 v117, v[2:5] offset:32768
	s_waitcnt lgkmcnt(3)
	v_mfma_f32_16x16x32_bf16 v[94:97], v[118:121], v[148:151], v[94:97]
	s_waitcnt lgkmcnt(2)
	v_mfma_f32_16x16x32_bf16 v[144:147], v[110:113], v[148:151], v[158:161]
	s_waitcnt vmcnt(14)
	ds_write_b128 v116, v[6:9] offset:49152
	s_waitcnt lgkmcnt(2)
	v_mfma_f32_16x16x32_bf16 v[90:93], v[126:129], v[148:151], v[90:93]
	v_mfma_f32_16x16x32_bf16 v[148:151], v[206:209], v[102:105], v[162:165]
	s_waitcnt vmcnt(13)
	ds_write_b128 v117, v[10:13] offset:36864
	v_mfma_f32_16x16x32_bf16 v[86:89], v[118:121], v[102:105], v[86:89]
	v_mfma_f32_16x16x32_bf16 v[158:161], v[110:113], v[102:105], v[198:201]
	s_waitcnt vmcnt(12)
	ds_write_b128 v116, v[14:17] offset:53248
	v_mfma_f32_16x16x32_bf16 v[82:85], v[126:129], v[102:105], v[82:85]
	v_mfma_f32_16x16x32_bf16 v[102:105], v[206:209], v[194:197], v[202:205]
	s_waitcnt vmcnt(11)
	ds_write_b128 v117, v[18:21] offset:40960
	v_mfma_f32_16x16x32_bf16 v[78:81], v[118:121], v[194:197], v[78:81]
	v_mfma_f32_16x16x32_bf16 v[162:165], v[110:113], v[194:197], v[210:213]
	s_waitcnt vmcnt(10)
	ds_write_b128 v116, v[22:25] offset:57344
	v_mfma_f32_16x16x32_bf16 v[70:73], v[126:129], v[194:197], v[70:73]
	v_mfma_f32_16x16x32_bf16 v[98:101], v[206:209], v[106:109], v[98:101]
	s_waitcnt vmcnt(9)
	ds_write_b128 v117, v[26:29] offset:45056
	v_mfma_f32_16x16x32_bf16 v[66:69], v[118:121], v[106:109], v[66:69]
	v_mfma_f32_16x16x32_bf16 v[110:113], v[110:113], v[106:109], v[132:135]
	s_waitcnt vmcnt(8)
	ds_write_b128 v116, v[30:33] offset:61440
	v_mfma_f32_16x16x32_bf16 v[74:77], v[126:129], v[106:109], v[74:77]
	s_setprio 0
	s_waitcnt lgkmcnt(0)
	s_barrier
	s_setprio 1
	ds_read_b128 v[26:29], v122 offset:49152
	ds_read_b128 v[10:13], v124 offset:32768
	ds_read_b128 v[18:21], v124 offset:34816
	ds_read_b128 v[30:33], v122 offset:51200
	ds_read_b128 v[106:109], v124 offset:36864
	ds_read_b128 v[114:117], v124 offset:38912
	ds_read_b128 v[118:121], v122 offset:53248
	ds_read_b128 v[124:127], v122 offset:55296
	s_waitcnt lgkmcnt(6)
	v_mfma_f32_16x16x32_bf16 v[132:135], v[26:29], v[10:13], v[140:143]
	global_load_dwordx4 v[2:5], v[180:181], off offset:128
	s_waitcnt lgkmcnt(4)
	v_mfma_f32_16x16x32_bf16 v[94:97], v[30:33], v[10:13], v[94:97]
	ds_read_b128 v[140:143], v123 offset:32768
	s_waitcnt lgkmcnt(2)
	v_mfma_f32_16x16x32_bf16 v[144:147], v[118:121], v[10:13], v[144:147]
	global_load_dwordx4 v[6:9], v[186:187], off offset:128
	s_waitcnt lgkmcnt(1)
	v_mfma_f32_16x16x32_bf16 v[90:93], v[124:127], v[10:13], v[90:93]
	ds_read_b128 v[194:197], v123 offset:34816
	v_mfma_f32_16x16x32_bf16 v[148:151], v[26:29], v[18:21], v[148:151]
	global_load_dwordx4 v[10:13], v[188:189], off offset:128
	v_mfma_f32_16x16x32_bf16 v[86:89], v[30:33], v[18:21], v[86:89]
	ds_read_b128 v[198:201], v123 offset:36864
	v_mfma_f32_16x16x32_bf16 v[158:161], v[118:121], v[18:21], v[158:161]
	global_load_dwordx4 v[14:17], v[174:175], off offset:128
	v_mfma_f32_16x16x32_bf16 v[82:85], v[124:127], v[18:21], v[82:85]
	ds_read_b128 v[202:205], v123 offset:38912
	v_mfma_f32_16x16x32_bf16 v[206:209], v[26:29], v[106:109], v[102:105]
	global_load_dwordx4 v[18:21], v[136:137], off offset:128
	v_mfma_f32_16x16x32_bf16 v[78:81], v[30:33], v[106:109], v[78:81]
	ds_read_b128 v[210:213], v130 offset:49152
	v_mfma_f32_16x16x32_bf16 v[162:165], v[118:121], v[106:109], v[162:165]
	global_load_dwordx4 v[22:25], v[176:177], off offset:128
	v_mfma_f32_16x16x32_bf16 v[70:73], v[124:127], v[106:109], v[70:73]
	ds_read_b128 v[214:217], v130 offset:51200
	v_mfma_f32_16x16x32_bf16 v[218:221], v[26:29], v[114:117], v[98:101]
	global_load_dwordx4 v[26:29], v[166:167], off offset:128
	v_mfma_f32_16x16x32_bf16 v[66:69], v[30:33], v[114:117], v[66:69]
	ds_read_b128 v[222:225], v130 offset:53248
	v_mfma_f32_16x16x32_bf16 v[226:229], v[118:121], v[114:117], v[110:113]
	global_load_dwordx4 v[30:33], v[178:179], off offset:128
	v_mfma_f32_16x16x32_bf16 v[230:233], v[124:127], v[114:117], v[74:77]
	s_waitcnt lgkmcnt(2)
	v_mfma_f32_16x16x32_bf16 v[126:129], v[210:213], v[140:143], v[132:135]
	s_nop 2
	ds_read_b128 v[130:133], v130 offset:55296
	s_waitcnt lgkmcnt(2)
	v_mfma_f32_16x16x32_bf16 v[122:125], v[214:217], v[140:143], v[94:97]
	s_waitcnt lgkmcnt(1)
	v_mfma_f32_16x16x32_bf16 v[118:121], v[222:225], v[140:143], v[144:147]
	s_waitcnt lgkmcnt(0)
	v_mfma_f32_16x16x32_bf16 v[114:117], v[130:133], v[140:143], v[90:93]
	v_mfma_f32_16x16x32_bf16 v[110:113], v[210:213], v[194:197], v[148:151]
	v_mfma_f32_16x16x32_bf16 v[106:109], v[214:217], v[194:197], v[86:89]
	v_mfma_f32_16x16x32_bf16 v[102:105], v[222:225], v[194:197], v[158:161]
	v_mfma_f32_16x16x32_bf16 v[98:101], v[130:133], v[194:197], v[82:85]
	v_mfma_f32_16x16x32_bf16 v[94:97], v[210:213], v[198:201], v[206:209]
	v_mfma_f32_16x16x32_bf16 v[90:93], v[214:217], v[198:201], v[78:81]
	v_mfma_f32_16x16x32_bf16 v[86:89], v[222:225], v[198:201], v[162:165]
	v_mfma_f32_16x16x32_bf16 v[82:85], v[130:133], v[198:201], v[70:73]
	v_mfma_f32_16x16x32_bf16 v[78:81], v[210:213], v[202:205], v[218:221]
	v_mfma_f32_16x16x32_bf16 v[74:77], v[214:217], v[202:205], v[66:69]
	v_mfma_f32_16x16x32_bf16 v[70:73], v[222:225], v[202:205], v[226:229]
	v_mfma_f32_16x16x32_bf16 v[66:69], v[130:133], v[202:205], v[230:233]
	s_setprio 0
	v_add_u32_e32 v134, s4, v152
	v_ashrrev_i32_e32 v135, 31, v134
	v_lshlrev_b64 v[136:137], 12, v[134:135]
	v_or_b32_e32 v140, s10, v153
	v_mov_b32_e32 v141, v1
	v_cndmask_b32_e64 v0, 0, 1, s[42:43]
	v_lshl_add_u64 v[130:131], s[40:41], 0, v[136:137]
	v_cmp_ne_u32_e64 s[38:39], 1, v0
	s_andn2_b64 vcc, exec, s[42:43]
	v_lshl_add_u64 v[146:147], v[140:141], 2, v[130:131]
	s_barrier
	s_cbranch_vccnz .LBB0_160
	global_load_dwordx4 v[130:133], v[146:147], off
	s_mov_b64 s[46:47], 0
	s_branch .LBB0_161

.LBB0_474:
	v_mov_b32_e32 v67, v169
	s_mov_b32 s11, s8
	v_lshrrev_b32_e32 v69, 4, v67
	v_ashrrev_i32_e32 v71, 3, v67
	v_lshrrev_b32_e32 v77, 1, v67
	v_and_b32_e32 v80, 4, v69
	v_and_b32_e32 v81, 3, v71
	v_and_b32_e32 v73, 7, v67
	v_xor_b32_e32 v75, v71, v67
	v_and_b32_e32 v77, 16, v77
	v_and_b32_e32 v79, 8, v69
	v_or_b32_e32 v82, v80, v81
	v_lshlrev_b32_e32 v75, 4, v75
	v_or3_b32 v77, v77, v79, v82
	v_bitop3_b32 v79, v80, v73, v81 bitop3:0x36
	v_lshlrev_b32_e32 v71, 7, v71
	v_lshlrev_b32_e32 v79, 4, v79
	v_and_or_b32 v115, v75, s24, v71
	v_lshl_or_b32 v114, v77, 7, v79
	s_waitcnt vmcnt(15)
	ds_write_b128 v115, v[34:37]
	s_waitcnt vmcnt(13)
	ds_write_b128 v114, v[38:41] offset:16384
	s_waitcnt vmcnt(11)
	ds_write_b128 v115, v[42:45] offset:4096
	s_waitcnt vmcnt(9)
	ds_write_b128 v114, v[46:49] offset:20480
	s_waitcnt vmcnt(7)
	ds_write_b128 v115, v[50:53] offset:8192
	s_waitcnt vmcnt(5)
	ds_write_b128 v114, v[54:57] offset:24576
	s_waitcnt vmcnt(3)
	ds_write_b128 v115, v[58:61] offset:12288
	s_waitcnt vmcnt(1)
	ds_write_b128 v114, v[62:65] offset:28672
	v_lshlrev_b32_e32 v35, 7, v67
	v_bfe_u32 v34, v67, 4, 2
	v_and_b32_e32 v36, 0x780, v35
	v_and_b32_e32 v116, 0x2780, v35
	v_bitop3_b32 v35, v69, v73, 3 bitop3:0x6c
	v_mov_b32_e32 v75, v1
	v_lshlrev_b32_e32 v117, 4, v35
	v_lshlrev_b32_e32 v35, 6, v67
	v_bitop3_b32 v34, v34, v73, 4 bitop3:0x36
	v_mov_b32_e32 v73, v1
	v_mov_b32_e32 v67, v1
	v_mov_b32_e32 v69, v1
	v_mov_b32_e32 v77, v1
	v_mov_b32_e32 v71, v1
	v_mov_b32_e32 v79, v1
	v_lshl_add_u64 v[100:101], v[74:75], 1, s[0:1]
	v_mov_b32_e32 v74, 0
	s_mov_b32 s16, s10
	v_and_or_b32 v118, v35, s30, v36
	v_lshlrev_b32_e32 v119, 4, v34
	v_lshl_add_u64 v[98:99], v[72:73], 1, s[0:1]
	v_lshl_add_u64 v[102:103], v[76:77], 1, s[0:1]
	v_lshl_add_u64 v[104:105], v[78:79], 1, s[0:1]
	v_lshlrev_b64 v[106:107], 1, v[0:1]
	s_waitcnt lgkmcnt(8)
	v_lshlrev_b64 v[108:109], 1, v[66:67]
	v_lshlrev_b64 v[110:111], 1, v[68:69]
	v_lshlrev_b64 v[112:113], 1, v[70:71]
	s_mov_b32 s8, -2
	s_mov_b64 s[28:29], s[34:35]
	v_mov_b32_e32 v75, v74
	v_mov_b32_e32 v76, v74
	v_mov_b32_e32 v77, v74
	v_mov_b32_e32 v62, v74
	v_mov_b32_e32 v63, v74
	v_mov_b32_e32 v64, v74
	v_mov_b32_e32 v65, v74
	v_mov_b32_e32 v66, v74
	v_mov_b32_e32 v67, v74
	v_mov_b32_e32 v68, v74
	v_mov_b32_e32 v69, v74
	v_mov_b32_e32 v58, v74
	v_mov_b32_e32 v59, v74
	v_mov_b32_e32 v60, v74
	v_mov_b32_e32 v61, v74
	v_mov_b32_e32 v70, v74
	v_mov_b32_e32 v71, v74
	v_mov_b32_e32 v72, v74
	v_mov_b32_e32 v73, v74
	v_mov_b32_e32 v54, v74
	v_mov_b32_e32 v55, v74
	v_mov_b32_e32 v56, v74
	v_mov_b32_e32 v57, v74
	v_mov_b32_e32 v78, v74
	v_mov_b32_e32 v79, v74
	v_mov_b32_e32 v80, v74
	v_mov_b32_e32 v81, v74
	v_mov_b32_e32 v50, v74
	v_mov_b32_e32 v51, v74
	v_mov_b32_e32 v52, v74
	v_mov_b32_e32 v53, v74
	v_mov_b32_e32 v82, v74
	v_mov_b32_e32 v83, v74
	v_mov_b32_e32 v84, v74
	v_mov_b32_e32 v85, v74
	v_mov_b32_e32 v46, v74
	v_mov_b32_e32 v47, v74
	v_mov_b32_e32 v48, v74
	v_mov_b32_e32 v49, v74
	v_mov_b32_e32 v86, v74
	v_mov_b32_e32 v87, v74
	v_mov_b32_e32 v88, v74
	v_mov_b32_e32 v89, v74
	v_mov_b32_e32 v42, v74
	v_mov_b32_e32 v43, v74
	v_mov_b32_e32 v44, v74
	v_mov_b32_e32 v45, v74
	v_mov_b32_e32 v90, v74
	v_mov_b32_e32 v91, v74
	v_mov_b32_e32 v92, v74
	v_mov_b32_e32 v93, v74
	v_mov_b32_e32 v38, v74
	v_mov_b32_e32 v39, v74
	v_mov_b32_e32 v40, v74
	v_mov_b32_e32 v41, v74
	v_mov_b32_e32 v94, v74
	v_mov_b32_e32 v95, v74
	v_mov_b32_e32 v96, v74
	v_mov_b32_e32 v97, v74
	v_mov_b32_e32 v34, v74
	v_mov_b32_e32 v35, v74
	v_mov_b32_e32 v36, v74
	v_mov_b32_e32 v37, v74
	s_waitcnt lgkmcnt(0)
	s_barrier
	v_readlane_b32 s100, v255, 36
	s_mul_i32 s100, s100, 0xa0
	s_and_b32 s101, s90, 7
	s_lshl_b32 s101, s101, 2
	s_add_u32 s100, s100, s101
	s_add_u32 s100, s100, 0x1a9d4bc0
	s_add_u32 s98, s72, s100
	s_addc_u32 s99, s73, 0
	v_mov_b32_e32 v240, 0x10200
	v_mov_b32_e32 v239, 1
	v_cmp_eq_u32_e32 vcc, 0, v169
	s_mov_b64 s[100:101], exec
	s_and_b64 exec, exec, vcc
	s_cbranch_execz .Ldyn_skip_3
	global_atomic_add v239, v1, v239, s[98:99] sc0

.LBB0_475:
	s_setprio 1
	s_add_u32 s98, s28, s17
	s_addc_u32 s99, s29, 0
	v_add_u32_e32 v120, v117, v116
	v_add_u32_e32 v122, v117, v118
	v_add_u32_e32 v121, v119, v118
	ds_read_b32 v241, v240
	ds_read_b128 v[124:127], v120 offset:16384
	ds_read_b128 v[144:147], v120 offset:18432
	ds_read_b128 v[156:159], v120 offset:20480
	ds_read_b128 v[160:163], v120 offset:22528
	ds_read_b128 v[128:131], v122
	ds_read_b128 v[132:135], v122 offset:2048
	ds_read_b128 v[148:151], v122 offset:4096
	ds_read_b128 v[152:155], v122 offset:6144
	s_waitcnt lgkmcnt(3)
	v_mfma_f32_16x16x32_bf16 v[34:37], v[124:127], v[128:131], v[34:37]
	global_load_dwordx4 v[164:167], v106, s[98:99] offset:256
	v_mfma_f32_16x16x32_bf16 v[94:97], v[144:147], v[128:131], v[94:97]
	ds_read_b128 v[194:197], v121
	v_mfma_f32_16x16x32_bf16 v[38:41], v[156:159], v[128:131], v[38:41]
	global_load_dwordx4 v[198:201], v98, s[28:29] offset:256
	v_mfma_f32_16x16x32_bf16 v[90:93], v[160:163], v[128:131], v[90:93]
	v_add_u32_e32 v130, v119, v116
	ds_read_b128 v[202:205], v121 offset:2048
	s_waitcnt lgkmcnt(4)
	v_mfma_f32_16x16x32_bf16 v[42:45], v[124:127], v[132:135], v[42:45]
	global_load_dwordx4 v[206:209], v108, s[98:99] offset:256
	v_mfma_f32_16x16x32_bf16 v[86:89], v[144:147], v[132:135], v[86:89]
	ds_read_b128 v[210:213], v121 offset:4096
	v_mfma_f32_16x16x32_bf16 v[46:49], v[156:159], v[132:135], v[46:49]
	global_load_dwordx4 v[214:217], v100, s[28:29] offset:256
	v_mfma_f32_16x16x32_bf16 v[82:85], v[160:163], v[132:135], v[82:85]
	ds_read_b128 v[132:135], v121 offset:6144
	s_waitcnt lgkmcnt(5)
	v_mfma_f32_16x16x32_bf16 v[50:53], v[124:127], v[148:151], v[50:53]
	global_load_dwordx4 v[218:221], v110, s[98:99] offset:256
	v_mfma_f32_16x16x32_bf16 v[78:81], v[144:147], v[148:151], v[78:81]
	ds_read_b128 v[222:225], v130 offset:16384
	v_mfma_f32_16x16x32_bf16 v[54:57], v[156:159], v[148:151], v[54:57]
	global_load_dwordx4 v[226:229], v102, s[28:29] offset:256
	v_mfma_f32_16x16x32_bf16 v[70:73], v[160:163], v[148:151], v[70:73]
	ds_read_b128 v[148:151], v130 offset:18432
	s_waitcnt lgkmcnt(6)
	v_mfma_f32_16x16x32_bf16 v[58:61], v[124:127], v[152:155], v[58:61]
	global_load_dwordx4 v[124:127], v112, s[98:99] offset:256
	v_mfma_f32_16x16x32_bf16 v[66:69], v[144:147], v[152:155], v[66:69]
	ds_read_b128 v[144:147], v130 offset:20480
	v_mfma_f32_16x16x32_bf16 v[62:65], v[156:159], v[152:155], v[62:65]
	global_load_dwordx4 v[156:159], v104, s[28:29] offset:256
	v_mfma_f32_16x16x32_bf16 v[74:77], v[160:163], v[152:155], v[74:77]
	ds_read_b128 v[152:155], v130 offset:22528
	s_waitcnt lgkmcnt(3)
	v_mfma_f32_16x16x32_bf16 v[34:37], v[222:225], v[194:197], v[34:37]
	s_waitcnt vmcnt(15)
	ds_write_b128 v115, v[2:5] offset:32768
	s_waitcnt lgkmcnt(3)
	v_mfma_f32_16x16x32_bf16 v[94:97], v[148:151], v[194:197], v[94:97]
	s_waitcnt lgkmcnt(2)
	v_mfma_f32_16x16x32_bf16 v[38:41], v[144:147], v[194:197], v[38:41]
	s_waitcnt vmcnt(14)
	ds_write_b128 v114, v[6:9] offset:49152
	s_waitcnt lgkmcnt(2)
	v_mfma_f32_16x16x32_bf16 v[90:93], v[152:155], v[194:197], v[90:93]
	v_mfma_f32_16x16x32_bf16 v[42:45], v[222:225], v[202:205], v[42:45]
	s_waitcnt vmcnt(13)
	ds_write_b128 v115, v[10:13] offset:36864
	v_mfma_f32_16x16x32_bf16 v[86:89], v[148:151], v[202:205], v[86:89]
	v_mfma_f32_16x16x32_bf16 v[46:49], v[144:147], v[202:205], v[46:49]
	s_waitcnt vmcnt(12)
	ds_write_b128 v114, v[14:17] offset:53248
	v_mfma_f32_16x16x32_bf16 v[82:85], v[152:155], v[202:205], v[82:85]
	v_mfma_f32_16x16x32_bf16 v[50:53], v[222:225], v[210:213], v[50:53]
	s_waitcnt vmcnt(11)
	ds_write_b128 v115, v[18:21] offset:40960
	v_mfma_f32_16x16x32_bf16 v[78:81], v[148:151], v[210:213], v[78:81]
	v_mfma_f32_16x16x32_bf16 v[54:57], v[144:147], v[210:213], v[54:57]
	s_waitcnt vmcnt(10)
	ds_write_b128 v114, v[22:25] offset:57344
	v_mfma_f32_16x16x32_bf16 v[70:73], v[152:155], v[210:213], v[70:73]
	v_mfma_f32_16x16x32_bf16 v[58:61], v[222:225], v[132:135], v[58:61]
	s_waitcnt vmcnt(9)
	ds_write_b128 v115, v[26:29] offset:45056
	v_mfma_f32_16x16x32_bf16 v[66:69], v[148:151], v[132:135], v[66:69]
	v_mfma_f32_16x16x32_bf16 v[62:65], v[144:147], v[132:135], v[62:65]
	s_waitcnt vmcnt(8)
	ds_write_b128 v114, v[30:33] offset:61440
	v_mfma_f32_16x16x32_bf16 v[74:77], v[152:155], v[132:135], v[74:77]
	s_setprio 0
	s_waitcnt lgkmcnt(0)
	s_barrier
	s_setprio 1
	ds_read_b128 v[26:29], v120 offset:49152
	ds_read_b128 v[30:33], v120 offset:51200
	ds_read_b128 v[148:151], v120 offset:53248
	ds_read_b128 v[152:155], v120 offset:55296
	ds_read_b128 v[10:13], v122 offset:32768
	ds_read_b128 v[18:21], v122 offset:34816
	ds_read_b128 v[132:135], v122 offset:36864
	ds_read_b128 v[144:147], v122 offset:38912
	s_waitcnt lgkmcnt(3)
	v_mfma_f32_16x16x32_bf16 v[34:37], v[26:29], v[10:13], v[34:37]
	global_load_dwordx4 v[2:5], v106, s[98:99] offset:384
	v_mfma_f32_16x16x32_bf16 v[94:97], v[30:33], v[10:13], v[94:97]
	ds_read_b128 v[160:163], v121 offset:32768
	v_mfma_f32_16x16x32_bf16 v[38:41], v[148:151], v[10:13], v[38:41]
	global_load_dwordx4 v[6:9], v98, s[28:29] offset:384
	v_mfma_f32_16x16x32_bf16 v[90:93], v[152:155], v[10:13], v[90:93]
	ds_read_b128 v[194:197], v121 offset:34816
	s_waitcnt lgkmcnt(4)
	v_mfma_f32_16x16x32_bf16 v[42:45], v[26:29], v[18:21], v[42:45]
	global_load_dwordx4 v[10:13], v108, s[98:99] offset:384
	v_mfma_f32_16x16x32_bf16 v[86:89], v[30:33], v[18:21], v[86:89]
	ds_read_b128 v[202:205], v121 offset:36864
	v_mfma_f32_16x16x32_bf16 v[46:49], v[148:151], v[18:21], v[46:49]
	global_load_dwordx4 v[14:17], v100, s[28:29] offset:384
	v_mfma_f32_16x16x32_bf16 v[82:85], v[152:155], v[18:21], v[82:85]
	ds_read_b128 v[210:213], v121 offset:38912
	s_waitcnt lgkmcnt(5)
	v_mfma_f32_16x16x32_bf16 v[50:53], v[26:29], v[132:135], v[50:53]
	global_load_dwordx4 v[18:21], v110, s[98:99] offset:384
	v_mfma_f32_16x16x32_bf16 v[78:81], v[30:33], v[132:135], v[78:81]
	ds_read_b128 v[222:225], v130 offset:49152
	v_mfma_f32_16x16x32_bf16 v[54:57], v[148:151], v[132:135], v[54:57]
	global_load_dwordx4 v[22:25], v102, s[28:29] offset:384
	v_mfma_f32_16x16x32_bf16 v[70:73], v[152:155], v[132:135], v[70:73]
	ds_read_b128 v[132:135], v130 offset:51200
	s_waitcnt lgkmcnt(6)
	v_mfma_f32_16x16x32_bf16 v[58:61], v[26:29], v[144:147], v[58:61]
	global_load_dwordx4 v[26:29], v112, s[98:99] offset:384
	v_mfma_f32_16x16x32_bf16 v[66:69], v[30:33], v[144:147], v[66:69]
	ds_read_b128 v[230:233], v130 offset:53248
	v_mfma_f32_16x16x32_bf16 v[62:65], v[148:151], v[144:147], v[62:65]
	global_load_dwordx4 v[30:33], v104, s[28:29] offset:384
	v_mfma_f32_16x16x32_bf16 v[74:77], v[152:155], v[144:147], v[74:77]
	ds_read_b128 v[144:147], v130 offset:55296
	s_waitcnt lgkmcnt(3)
	v_mfma_f32_16x16x32_bf16 v[34:37], v[222:225], v[160:163], v[34:37]
	s_waitcnt vmcnt(15)
	ds_write_b128 v115, v[164:167]
	s_waitcnt lgkmcnt(3)
	v_mfma_f32_16x16x32_bf16 v[94:97], v[132:135], v[160:163], v[94:97]
	s_waitcnt lgkmcnt(2)
	v_mfma_f32_16x16x32_bf16 v[38:41], v[230:233], v[160:163], v[38:41]
	s_waitcnt vmcnt(14)
	ds_write_b128 v114, v[198:201] offset:16384
	s_waitcnt lgkmcnt(2)
	v_mfma_f32_16x16x32_bf16 v[90:93], v[144:147], v[160:163], v[90:93]
	v_mfma_f32_16x16x32_bf16 v[42:45], v[222:225], v[194:197], v[42:45]
	s_waitcnt vmcnt(13)
	ds_write_b128 v115, v[206:209] offset:4096
	v_mfma_f32_16x16x32_bf16 v[86:89], v[132:135], v[194:197], v[86:89]
	v_mfma_f32_16x16x32_bf16 v[46:49], v[230:233], v[194:197], v[46:49]
	s_waitcnt vmcnt(12)
	ds_write_b128 v114, v[214:217] offset:20480
	v_mfma_f32_16x16x32_bf16 v[82:85], v[144:147], v[194:197], v[82:85]
	v_mfma_f32_16x16x32_bf16 v[50:53], v[222:225], v[202:205], v[50:53]
	s_waitcnt vmcnt(11)
	ds_write_b128 v115, v[218:221] offset:8192
	v_mfma_f32_16x16x32_bf16 v[78:81], v[132:135], v[202:205], v[78:81]
	v_mfma_f32_16x16x32_bf16 v[54:57], v[230:233], v[202:205], v[54:57]
	s_waitcnt vmcnt(10)
	ds_write_b128 v114, v[226:229] offset:24576
	v_mfma_f32_16x16x32_bf16 v[70:73], v[144:147], v[202:205], v[70:73]
	v_mfma_f32_16x16x32_bf16 v[58:61], v[222:225], v[210:213], v[58:61]
	s_waitcnt vmcnt(9)
	ds_write_b128 v115, v[124:127] offset:12288
	v_mfma_f32_16x16x32_bf16 v[66:69], v[132:135], v[210:213], v[66:69]
	v_mfma_f32_16x16x32_bf16 v[62:65], v[230:233], v[210:213], v[62:65]
	s_waitcnt vmcnt(8)
	ds_write_b128 v114, v[156:159] offset:28672
	v_mfma_f32_16x16x32_bf16 v[74:77], v[144:147], v[210:213], v[74:77]
	s_mov_b64 exec, vcc
	ds_write_b32 v240, v239
	s_mov_b64 exec, -1
	s_setprio 0
	s_add_i32 s8, s8, 2
	s_add_u32 s28, s28, 0x100
	s_addc_u32 s29, s29, 0
	s_cmp_lt_u32 s8, 12
	s_waitcnt lgkmcnt(0)
	s_barrier
	s_cbranch_scc1 .LBB0_475
	v_readfirstlane_b32 s8, v241
	s_nop 3
	s_add_i32 s8, s8, s2
	s_cmpk_lt_u32 s8, 0x420
	s_cselect_b64 s[56:57], -1, 0
	s_and_b64 s[14:15], s[56:57], exec
	s_cselect_b32 s10, s8, s11
	s_mul_hi_u32 s11, s10, 0x3e0f83e1
	s_lshr_b32 s11, s11, 6
	s_mul_i32 s14, s11, 0x108
	v_mov_b32_e32 v0, v169
	s_sub_i32 s10, s10, s14
	s_lshl_b32 s11, s11, 3
	s_add_i32 s11, s11, s21
	s_and_b32 s14, s10, 7
	v_lshlrev_b32_e32 v98, 3, v0
	v_lshlrev_b32_e32 v0, 7, v0
	s_or_b32 s11, s11, s14
	v_and_b32_e32 v0, 0xfffffc00, v0
	v_lshl_add_u32 v0, s11, 17, v0
	v_and_or_b32 v0, v98, 56, v0
	v_mov_b32_e32 v98, v169
	s_lshl_b32 s10, s10, 4
	s_and_b32 s10, s10, 0x1f80
	v_lshrrev_b32_e32 v99, 3, v98
	v_lshlrev_b32_e32 v98, 3, v98
	v_add_u32_e32 v99, s10, v99
	v_and_b32_e32 v98, 56, v98
	v_add_u32_e32 v128, 0x8000, v0
	v_add_u32_e32 v136, 0x10000, v0
	v_lshl_or_b32 v160, v99, 10, v98
	v_add_u32_e32 v210, 0x18000, v0
	v_add_u32_e32 v198, 0x8000, v160
	v_add_u32_e32 v212, 0x10000, v160
	v_add_u32_e32 v214, 0x18000, v160
	s_setprio 1
	ds_read_b128 v[98:101], v120 offset:16384
	ds_read_b128 v[110:113], v120 offset:18432
	ds_read_b128 v[132:135], v120 offset:20480
	ds_read_b128 v[144:147], v120 offset:22528
	ds_read_b128 v[102:105], v122
	ds_read_b128 v[106:109], v122 offset:2048
	ds_read_b128 v[116:119], v122 offset:4096
	ds_read_b128 v[124:127], v122 offset:6144
	v_mov_b32_e32 v161, v1
	v_mov_b32_e32 v129, v1
	v_mov_b32_e32 v199, v1
	v_mov_b32_e32 v137, v1
	v_mov_b32_e32 v213, v1
	v_mov_b32_e32 v211, v1
	v_mov_b32_e32 v215, v1
	v_lshl_add_u64 v[216:217], v[0:1], 1, s[48:49]
	v_lshl_add_u64 v[218:219], v[160:161], 1, s[50:51]
	v_lshl_add_u64 v[220:221], v[128:129], 1, s[48:49]
	v_lshl_add_u64 v[222:223], v[198:199], 1, s[50:51]
	v_lshl_add_u64 v[136:137], v[136:137], 1, s[48:49]
	v_lshl_add_u64 v[212:213], v[212:213], 1, s[50:51]
	v_lshl_add_u64 v[224:225], v[210:211], 1, s[48:49]
	v_lshl_add_u64 v[226:227], v[214:215], 1, s[50:51]
	s_waitcnt lgkmcnt(3)
	v_mfma_f32_16x16x32_bf16 v[148:151], v[98:101], v[102:105], v[34:37]
	s_nop 2
	global_load_dwordx4 v[34:37], v[216:217], off
	v_mfma_f32_16x16x32_bf16 v[94:97], v[110:113], v[102:105], v[94:97]
	ds_read_b128 v[152:155], v121
	v_mfma_f32_16x16x32_bf16 v[156:159], v[132:135], v[102:105], v[38:41]
	s_nop 2
	global_load_dwordx4 v[38:41], v[218:219], off
	v_mfma_f32_16x16x32_bf16 v[90:93], v[144:147], v[102:105], v[90:93]
	ds_read_b128 v[102:105], v121 offset:2048
	s_waitcnt lgkmcnt(4)
	v_mfma_f32_16x16x32_bf16 v[160:163], v[98:101], v[106:109], v[42:45]
	s_nop 2
	global_load_dwordx4 v[42:45], v[220:221], off
	v_mfma_f32_16x16x32_bf16 v[86:89], v[110:113], v[106:109], v[86:89]
	ds_read_b128 v[164:167], v121 offset:4096
	v_mfma_f32_16x16x32_bf16 v[194:197], v[132:135], v[106:109], v[46:49]
	s_nop 2
	global_load_dwordx4 v[46:49], v[222:223], off
	v_mfma_f32_16x16x32_bf16 v[82:85], v[144:147], v[106:109], v[82:85]
	ds_read_b128 v[106:109], v121 offset:6144
	s_waitcnt lgkmcnt(5)
	v_mfma_f32_16x16x32_bf16 v[198:201], v[98:101], v[116:119], v[50:53]
	s_nop 2
	global_load_dwordx4 v[50:53], v[136:137], off
	v_mfma_f32_16x16x32_bf16 v[78:81], v[110:113], v[116:119], v[78:81]
	ds_read_b128 v[202:205], v130 offset:16384
	v_mfma_f32_16x16x32_bf16 v[206:209], v[132:135], v[116:119], v[54:57]
	s_nop 2
	global_load_dwordx4 v[54:57], v[212:213], off
	v_mfma_f32_16x16x32_bf16 v[70:73], v[144:147], v[116:119], v[70:73]
	ds_read_b128 v[116:119], v130 offset:18432
	s_waitcnt lgkmcnt(6)
	v_mfma_f32_16x16x32_bf16 v[98:101], v[98:101], v[124:127], v[58:61]
	s_nop 2
	global_load_dwordx4 v[58:61], v[224:225], off
	v_mfma_f32_16x16x32_bf16 v[66:69], v[110:113], v[124:127], v[66:69]
	ds_read_b128 v[110:113], v130 offset:20480
	v_mfma_f32_16x16x32_bf16 v[132:135], v[132:135], v[124:127], v[62:65]
	s_nop 2
	global_load_dwordx4 v[62:65], v[226:227], off
	v_mfma_f32_16x16x32_bf16 v[74:77], v[144:147], v[124:127], v[74:77]
	ds_read_b128 v[124:127], v130 offset:22528
	s_waitcnt lgkmcnt(3)
	v_mfma_f32_16x16x32_bf16 v[144:147], v[202:205], v[152:155], v[148:151]
	s_waitcnt vmcnt(15)
	ds_write_b128 v115, v[2:5] offset:32768
	s_waitcnt lgkmcnt(3)
	v_mfma_f32_16x16x32_bf16 v[94:97], v[116:119], v[152:155], v[94:97]
	s_waitcnt lgkmcnt(2)
	v_mfma_f32_16x16x32_bf16 v[148:151], v[110:113], v[152:155], v[156:159]
	s_waitcnt vmcnt(14)
	ds_write_b128 v114, v[6:9] offset:49152
	s_waitcnt lgkmcnt(2)
	v_mfma_f32_16x16x32_bf16 v[90:93], v[124:127], v[152:155], v[90:93]
	v_mfma_f32_16x16x32_bf16 v[152:155], v[202:205], v[102:105], v[160:163]
	s_waitcnt vmcnt(13)
	ds_write_b128 v115, v[10:13] offset:36864
	v_mfma_f32_16x16x32_bf16 v[86:89], v[116:119], v[102:105], v[86:89]
	v_mfma_f32_16x16x32_bf16 v[156:159], v[110:113], v[102:105], v[194:197]
	s_waitcnt vmcnt(12)
	ds_write_b128 v114, v[14:17] offset:53248
	v_mfma_f32_16x16x32_bf16 v[82:85], v[124:127], v[102:105], v[82:85]
	v_mfma_f32_16x16x32_bf16 v[102:105], v[202:205], v[164:167], v[198:201]
	s_waitcnt vmcnt(11)
	ds_write_b128 v115, v[18:21] offset:40960
	v_mfma_f32_16x16x32_bf16 v[78:81], v[116:119], v[164:167], v[78:81]
	v_mfma_f32_16x16x32_bf16 v[160:163], v[110:113], v[164:167], v[206:209]
	s_waitcnt vmcnt(10)
	ds_write_b128 v114, v[22:25] offset:57344
	v_mfma_f32_16x16x32_bf16 v[70:73], v[124:127], v[164:167], v[70:73]
	v_mfma_f32_16x16x32_bf16 v[98:101], v[202:205], v[106:109], v[98:101]
	s_waitcnt vmcnt(9)
	ds_write_b128 v115, v[26:29] offset:45056
	v_mfma_f32_16x16x32_bf16 v[66:69], v[116:119], v[106:109], v[66:69]
	v_mfma_f32_16x16x32_bf16 v[110:113], v[110:113], v[106:109], v[132:135]
	s_waitcnt vmcnt(8)
	ds_write_b128 v114, v[30:33] offset:61440
	v_mfma_f32_16x16x32_bf16 v[74:77], v[124:127], v[106:109], v[74:77]
	s_setprio 0
	s_waitcnt lgkmcnt(0)
	s_barrier
	s_setprio 1
	ds_read_b128 v[26:29], v120 offset:49152
	ds_read_b128 v[10:13], v122 offset:32768
	ds_read_b128 v[18:21], v122 offset:34816
	ds_read_b128 v[30:33], v120 offset:51200
	ds_read_b128 v[106:109], v122 offset:36864
	ds_read_b128 v[114:117], v122 offset:38912
	ds_read_b128 v[122:125], v120 offset:53248
	ds_read_b128 v[126:129], v120 offset:55296
	s_waitcnt lgkmcnt(6)
	v_mfma_f32_16x16x32_bf16 v[132:135], v[26:29], v[10:13], v[144:147]
	global_load_dwordx4 v[2:5], v[216:217], off offset:128
	s_waitcnt lgkmcnt(4)
	v_mfma_f32_16x16x32_bf16 v[94:97], v[30:33], v[10:13], v[94:97]
	ds_read_b128 v[144:147], v121 offset:32768
	s_waitcnt lgkmcnt(2)
	v_mfma_f32_16x16x32_bf16 v[148:151], v[122:125], v[10:13], v[148:151]
	global_load_dwordx4 v[6:9], v[218:219], off offset:128
	s_waitcnt lgkmcnt(1)
	v_mfma_f32_16x16x32_bf16 v[90:93], v[126:129], v[10:13], v[90:93]
	ds_read_b128 v[164:167], v121 offset:34816
	v_mfma_f32_16x16x32_bf16 v[152:155], v[26:29], v[18:21], v[152:155]
	global_load_dwordx4 v[10:13], v[220:221], off offset:128
	v_mfma_f32_16x16x32_bf16 v[86:89], v[30:33], v[18:21], v[86:89]
	ds_read_b128 v[194:197], v121 offset:36864
	v_mfma_f32_16x16x32_bf16 v[156:159], v[122:125], v[18:21], v[156:159]
	global_load_dwordx4 v[14:17], v[222:223], off offset:128
	v_mfma_f32_16x16x32_bf16 v[82:85], v[126:129], v[18:21], v[82:85]
	ds_read_b128 v[198:201], v121 offset:38912
	v_mfma_f32_16x16x32_bf16 v[202:205], v[26:29], v[106:109], v[102:105]
	global_load_dwordx4 v[18:21], v[136:137], off offset:128
	v_mfma_f32_16x16x32_bf16 v[78:81], v[30:33], v[106:109], v[78:81]
	ds_read_b128 v[206:209], v130 offset:49152
	v_mfma_f32_16x16x32_bf16 v[160:163], v[122:125], v[106:109], v[160:163]
	global_load_dwordx4 v[22:25], v[212:213], off offset:128
	v_mfma_f32_16x16x32_bf16 v[70:73], v[126:129], v[106:109], v[70:73]
	ds_read_b128 v[210:213], v130 offset:51200
	v_mfma_f32_16x16x32_bf16 v[214:217], v[26:29], v[114:117], v[98:101]
	global_load_dwordx4 v[26:29], v[224:225], off offset:128
	v_mfma_f32_16x16x32_bf16 v[66:69], v[30:33], v[114:117], v[66:69]
	ds_read_b128 v[218:221], v130 offset:53248
	v_mfma_f32_16x16x32_bf16 v[222:225], v[122:125], v[114:117], v[110:113]
	global_load_dwordx4 v[30:33], v[226:227], off offset:128
	v_mfma_f32_16x16x32_bf16 v[226:229], v[126:129], v[114:117], v[74:77]
	s_waitcnt lgkmcnt(2)
	v_mfma_f32_16x16x32_bf16 v[126:129], v[206:209], v[144:147], v[132:135]
	s_nop 2
	ds_read_b128 v[130:133], v130 offset:55296
	s_waitcnt lgkmcnt(2)
	v_mfma_f32_16x16x32_bf16 v[122:125], v[210:213], v[144:147], v[94:97]
	s_waitcnt lgkmcnt(1)
	v_mfma_f32_16x16x32_bf16 v[118:121], v[218:221], v[144:147], v[148:151]
	s_waitcnt lgkmcnt(0)
	v_mfma_f32_16x16x32_bf16 v[114:117], v[130:133], v[144:147], v[90:93]
	v_mfma_f32_16x16x32_bf16 v[110:113], v[206:209], v[164:167], v[152:155]
	v_mfma_f32_16x16x32_bf16 v[106:109], v[210:213], v[164:167], v[86:89]
	v_mfma_f32_16x16x32_bf16 v[102:105], v[218:221], v[164:167], v[156:159]
	v_mfma_f32_16x16x32_bf16 v[98:101], v[130:133], v[164:167], v[82:85]
	v_mfma_f32_16x16x32_bf16 v[94:97], v[206:209], v[194:197], v[202:205]
	v_mfma_f32_16x16x32_bf16 v[90:93], v[210:213], v[194:197], v[78:81]
	v_mfma_f32_16x16x32_bf16 v[86:89], v[218:221], v[194:197], v[160:163]
	v_mfma_f32_16x16x32_bf16 v[82:85], v[130:133], v[194:197], v[70:73]
	v_mfma_f32_16x16x32_bf16 v[74:77], v[206:209], v[198:201], v[214:217]
	v_mfma_f32_16x16x32_bf16 v[70:73], v[210:213], v[198:201], v[66:69]
	v_mfma_f32_16x16x32_bf16 v[66:69], v[218:221], v[198:201], v[222:225]
	v_mfma_f32_16x16x32_bf16 v[78:81], v[130:133], v[198:201], v[226:229]
	s_setprio 0
	s_cmpk_gt_u32 s16, 0x9ff
	s_cselect_b64 s[42:43], -1, 0
	s_and_b32 s17, s16, 0x1f00
	s_cmpk_eq_i32 s17, 0xe00
	s_cselect_b64 s[40:41], -1, 0
	s_cmpk_gt_u32 s16, 0x5ff
	s_cselect_b64 s[46:47], -1, 0
	s_cmpk_gt_u32 s16, 0xbff
	s_cselect_b64 s[62:63], -1, 0
	s_cmpk_lt_u32 s16, 0xd00
	s_cselect_b64 s[14:15], -1, 0
	s_and_b64 s[26:27], s[14:15], exec
	s_movk_i32 s21, 0xf300
	s_cselect_b32 s28, 0xfffff400, s21
	s_nor_b64 s[60:61], s[14:15], s[40:41]
	s_cmpk_gt_u32 s16, 0xfff
	s_cselect_b64 s[58:59], -1, 0
	s_cmpk_lt_u32 s16, 0xe00
	v_add_u32_e32 v0, s9, v141
	s_cselect_b64 s[14:15], -1, 0
	v_or_b32_e32 v136, v0, v140
	s_movk_i32 s21, 0xc0
	s_and_b64 s[14:15], s[14:15], exec
	v_mad_i64_i32 v[134:135], s[26:27], v136, s21, 0
	s_movk_i32 s21, 0x1fcf
	s_movk_i32 s14, 0xf100
	v_bitop3_b32 v144, v0, s21, v140 bitop3:0xc8
	v_ashrrev_i32_e32 v0, 5, v0
	s_cselect_b32 s15, 0xfffff300, s14
	s_mov_b32 s14, 0x18991000
	v_ashrrev_i32_e32 v137, 31, v136
	v_and_b32_e32 v0, 0xffffff00, v0
	s_cselect_b32 s14, s14, 0x19991000
	v_add_u32_e32 v145, s15, v0
	v_lshlrev_b64 v[132:133], 10, v[136:137]
	v_lshlrev_b64 v[130:131], 11, v[136:137]
	v_or_b32_e32 v0, s16, v142
	s_mov_b64 s[44:45], -1
	s_and_b64 vcc, exec, s[46:47]
	s_barrier
	s_cbranch_vccz .LBB0_496
	s_and_b64 vcc, exec, s[42:43]
	s_cbranch_vccz .LBB0_493
	s_and_b64 vcc, exec, s[62:63]
	s_cbranch_vccz .LBB0_490
	s_and_b64 vcc, exec, s[60:61]
	s_cbranch_vccz .LBB0_487
	s_and_b64 vcc, exec, s[58:59]
	s_cbranch_vccz .LBB0_484
	v_cmp_gt_u32_e32 vcc, s7, v0
	s_and_saveexec_b64 s[44:45], vcc
	s_cbranch_execz .LBB0_483
	v_mul_f32_e32 v137, 0xbfb8aa3b, v126
	v_exp_f32_e32 v137, v137
	v_mul_f32_e32 v143, 0xbfb8aa3b, v127
	v_exp_f32_e32 v143, v143
	v_mul_f32_e32 v147, 0xbfb8aa3b, v129
	v_add_f32_e32 v137, 1.0, v137
	v_rcp_f32_e32 v146, v137
	v_mul_f32_e32 v137, 0xbfb8aa3b, v128
	v_exp_f32_e32 v137, v137
	v_exp_f32_e32 v149, v147
	v_add_f32_e32 v143, 1.0, v143
	v_rcp_f32_e32 v147, v143
	v_add_f32_e32 v137, 1.0, v137
	v_mul_f32_e32 v143, 0xbfb8aa3b, v122
	v_rcp_f32_e32 v148, v137
	v_add_f32_e32 v137, 1.0, v149
	v_exp_f32_e32 v143, v143
	v_mul_f32_e32 v149, 0xbfb8aa3b, v123
	v_exp_f32_e32 v151, v149
	v_rcp_f32_e32 v149, v137
	v_add_f32_e32 v137, 1.0, v143
	v_mul_f32_e32 v143, 0xbfb8aa3b, v124
	v_rcp_f32_e32 v150, v137
	v_add_f32_e32 v137, 1.0, v151
	v_exp_f32_e32 v143, v143
	v_mul_f32_e32 v151, 0xbfb8aa3b, v125
	v_exp_f32_e32 v153, v151
	v_rcp_f32_e32 v151, v137
	v_add_f32_e32 v137, 1.0, v143
	v_rcp_f32_e32 v152, v137
	v_add_f32_e32 v137, 1.0, v153
	v_lshl_add_u64 v[154:155], s[34:35], 0, v[134:135]
	v_rcp_f32_e32 v153, v137
	v_lshl_add_u64 v[154:155], v[0:1], 2, v[154:155]
	v_add_co_u32_e32 v154, vcc, 0x438d000, v154
	s_nop 1
	v_addc_co_u32_e32 v155, vcc, 0, v155, vcc
	global_store_dwordx4 v[154:155], v[146:149], off
	global_store_dwordx4 v[154:155], v[150:153], off offset:16
